# GQA attention loop: row sums via 16x16x32 bf16 MFMA with ones-selector B (no in-loop v_add), plus batched epilogue loads/bpermutes
# speedup vs baseline: 1.0111x; 1.0111x over previous
; #define LAS __attribute__((address_space(3)))
; __global__ void __launch_bounds__(NWAVES * 64, 2) fwd_megakernel(Params P) {
;     ...
;         const float sref = *(const float*)(ws + WS_LAM + 4);
;         if (diff) {
;             const unsigned* kq = (const unsigned*)(ws + WS_BAR) + 3800;
;             float bmx = -3.0e38f, bmn = 3.0e38f;
;             for (int b = 0; b < 32; ++b) { const float v = P.in[4][b * 4 + head] * LOG2E; bmx = fmaxf(bmx, v); bmn = fminf(bmn, v); }
;             const int si = s * 8 + head * 2;
;             const float qk0 = __builtin_sqrtf(__uint_as_float(kq[si]) * __uint_as_float(kq[48 + si])), qk1 = __builtin_sqrtf(__uint_as_float(kq[si + 1]) * __uint_as_float(kq[48 + si + 1]));
;             if (2.0f * fmaxf(qk0, qk1) + (bmx - bmn) <= 100.0f) att2::attn_unit<4, true, true>((LAS char*)lds, P, s, head, qb, bmx);
.LBB0_506:
	s_mov_b32 s73, s15
	s_lshl_b64 s[4:5], s[72:73], 2
	s_add_u32 s74, s44, s4
	s_addc_u32 s75, s45, s5
	global_load_dword v48, v0, s[74:75]
	global_load_dword v49, v0, s[74:75] offset:16
	global_load_dword v50, v0, s[74:75] offset:32
	global_load_dword v51, v0, s[74:75] offset:48
	global_load_dword v52, v0, s[74:75] offset:64
	global_load_dword v53, v0, s[74:75] offset:80
	global_load_dword v54, v0, s[74:75] offset:96
	global_load_dword v55, v0, s[74:75] offset:112
	global_load_dword v56, v0, s[74:75] offset:128
	global_load_dword v57, v0, s[74:75] offset:144
	global_load_dword v58, v0, s[74:75] offset:160
	global_load_dword v59, v0, s[74:75] offset:176
	global_load_dword v60, v0, s[74:75] offset:192
	global_load_dword v61, v0, s[74:75] offset:208
	global_load_dword v62, v0, s[74:75] offset:224
	global_load_dword v63, v0, s[74:75] offset:240
	global_load_dword v64, v0, s[74:75] offset:256
	global_load_dword v65, v0, s[74:75] offset:272
	global_load_dword v66, v0, s[74:75] offset:288
	global_load_dword v67, v0, s[74:75] offset:304
	global_load_dword v68, v0, s[74:75] offset:320
	global_load_dword v69, v0, s[74:75] offset:336
	global_load_dword v70, v0, s[74:75] offset:352
	global_load_dword v71, v0, s[74:75] offset:368
	global_load_dword v72, v0, s[74:75] offset:384
	global_load_dword v73, v0, s[74:75] offset:400
	global_load_dword v74, v0, s[74:75] offset:416
	global_load_dword v75, v0, s[74:75] offset:432
	global_load_dword v76, v0, s[74:75] offset:448
	global_load_dword v77, v0, s[74:75] offset:464
	global_load_dword v78, v0, s[74:75] offset:480
	global_load_dword v79, v0, s[74:75] offset:496
	s_lshl_b32 s54, s72, 1
	s_lshl_b32 s4, s64, 3
	s_add_i32 s14, s4, s54
	s_lshl_b64 s[4:5], s[14:15], 2
	s_add_u32 s4, s0, s4
	s_addc_u32 s5, s1, s5
	s_lshl_b32 s6, s64, 14
	global_load_dwordx2 v[2:3], v0, s[4:5]
	global_load_dwordx2 v[4:5], v0, s[4:5] offset:192
	s_waitcnt vmcnt(2)
	v_mul_f32_e32 v48, 0x3fb8aa3b, v48
	v_mul_f32_e32 v49, 0x3fb8aa3b, v49
	v_mul_f32_e32 v50, 0x3fb8aa3b, v50
	v_mul_f32_e32 v51, 0x3fb8aa3b, v51
	v_mul_f32_e32 v52, 0x3fb8aa3b, v52
	v_mul_f32_e32 v53, 0x3fb8aa3b, v53
	v_mul_f32_e32 v54, 0x3fb8aa3b, v54
	v_mul_f32_e32 v55, 0x3fb8aa3b, v55
	v_mul_f32_e32 v56, 0x3fb8aa3b, v56
	v_mul_f32_e32 v57, 0x3fb8aa3b, v57
	v_mul_f32_e32 v58, 0x3fb8aa3b, v58
	v_mul_f32_e32 v59, 0x3fb8aa3b, v59
	v_mul_f32_e32 v60, 0x3fb8aa3b, v60
	v_mul_f32_e32 v61, 0x3fb8aa3b, v61
	v_mul_f32_e32 v62, 0x3fb8aa3b, v62
	v_mul_f32_e32 v63, 0x3fb8aa3b, v63
	v_mul_f32_e32 v64, 0x3fb8aa3b, v64
	v_mul_f32_e32 v65, 0x3fb8aa3b, v65
	v_mul_f32_e32 v66, 0x3fb8aa3b, v66
	v_mul_f32_e32 v67, 0x3fb8aa3b, v67
	v_mul_f32_e32 v68, 0x3fb8aa3b, v68
	v_mul_f32_e32 v69, 0x3fb8aa3b, v69
	v_mul_f32_e32 v70, 0x3fb8aa3b, v70
	v_mul_f32_e32 v71, 0x3fb8aa3b, v71
	v_mul_f32_e32 v72, 0x3fb8aa3b, v72
	v_mul_f32_e32 v73, 0x3fb8aa3b, v73
	v_mul_f32_e32 v74, 0x3fb8aa3b, v74
	v_mul_f32_e32 v75, 0x3fb8aa3b, v75
	v_mul_f32_e32 v76, 0x3fb8aa3b, v76
	v_mul_f32_e32 v77, 0x3fb8aa3b, v77
	v_mul_f32_e32 v78, 0x3fb8aa3b, v78
	v_mul_f32_e32 v79, 0x3fb8aa3b, v79
	v_max3_f32 v1, v48, v49, v50
	v_min3_f32 v6, v48, v49, v50
	v_max3_f32 v1, v1, v51, v52
	v_min3_f32 v6, v6, v51, v52
	v_max3_f32 v1, v1, v53, v54
	v_min3_f32 v6, v6, v53, v54
	v_max3_f32 v1, v1, v55, v56
	v_min3_f32 v6, v6, v55, v56
	v_max3_f32 v1, v1, v57, v58
	v_min3_f32 v6, v6, v57, v58
	v_max3_f32 v1, v1, v59, v60
	v_min3_f32 v6, v6, v59, v60
	v_max3_f32 v1, v1, v61, v62
	v_min3_f32 v6, v6, v61, v62
	v_max3_f32 v1, v1, v63, v64
	v_min3_f32 v6, v6, v63, v64
	v_max3_f32 v1, v1, v65, v66
	v_min3_f32 v6, v6, v65, v66
	v_max3_f32 v1, v1, v67, v68
	v_min3_f32 v6, v6, v67, v68
	v_max3_f32 v1, v1, v69, v70
	v_min3_f32 v6, v6, v69, v70
	v_max3_f32 v1, v1, v71, v72
	v_min3_f32 v6, v6, v71, v72
	v_max3_f32 v1, v1, v73, v74
	v_min3_f32 v6, v6, v73, v74
	v_max3_f32 v1, v1, v75, v76
	v_min3_f32 v6, v6, v75, v76
	v_max3_f32 v1, v1, v77, v78
	v_min3_f32 v6, v6, v77, v78
	v_max3_f32 v1, v1, v79, v79
	v_min3_f32 v6, v6, v79, v79
	s_waitcnt vmcnt(0)
	v_mul_f32_e32 v2, v2, v4
	v_cmp_gt_f32_e32 vcc, s62, v2
	v_mul_f32_e32 v4, 0x4f800000, v2
	v_mul_f32_e32 v3, v3, v5
	v_cndmask_b32_e32 v2, v2, v4, vcc
	v_sqrt_f32_e32 v4, v2
	s_nop 0
	v_add_u32_e32 v7, -1, v4
	v_fma_f32 v8, -v7, v4, v2
	v_cmp_ge_f32_e64 s[4:5], 0, v8
	v_add_u32_e32 v8, 1, v4
	s_nop 0
	v_cndmask_b32_e64 v7, v4, v7, s[4:5]
	v_fma_f32 v4, -v8, v4, v2
	v_cmp_lt_f32_e64 s[4:5], 0, v4
	s_nop 1
	v_cndmask_b32_e64 v4, v7, v8, s[4:5]
	v_mul_f32_e32 v7, 0x37800000, v4
	v_cndmask_b32_e32 v4, v4, v7, vcc
	v_cmp_class_f32_e32 vcc, v2, v232
	s_nop 1
	v_cndmask_b32_e32 v2, v4, v2, vcc
	v_cmp_gt_f32_e32 vcc, s62, v3
	v_mul_f32_e32 v4, 0x4f800000, v3
	s_nop 0
	v_cndmask_b32_e32 v3, v3, v4, vcc
	v_sqrt_f32_e32 v4, v3
	s_nop 0
	v_add_u32_e32 v5, -1, v4
	v_fma_f32 v7, -v5, v4, v3
	v_cmp_ge_f32_e64 s[4:5], 0, v7
	v_add_u32_e32 v7, 1, v4
	s_nop 0
	v_cndmask_b32_e64 v5, v4, v5, s[4:5]
	v_fma_f32 v4, -v7, v4, v3
	v_cmp_lt_f32_e64 s[4:5], 0, v4
	s_nop 1
	v_cndmask_b32_e64 v4, v5, v7, s[4:5]
	v_mul_f32_e32 v5, 0x37800000, v4
	v_cndmask_b32_e32 v4, v4, v5, vcc
	v_cmp_class_f32_e32 vcc, v3, v232
	s_mov_b32 s4, 0x42c80000
	s_nop 0
	v_cndmask_b32_e32 v3, v4, v3, vcc
	v_max_f32_e32 v2, v2, v3
	v_sub_f32_e32 v3, v1, v6
	v_fmac_f32_e32 v3, 2.0, v2
	v_cmp_nge_f32_e32 vcc, s4, v3
	s_lshl_b32 s4, s64, 12
	s_add_i32 s7, s4, 0x6000
	s_cmp_lt_u32 s64, 2
	s_cselect_b64 s[78:79], -1, 0
	s_and_b64 s[4:5], s[78:79], exec
	s_cselect_b32 s56, s17, 0x1000
	s_cselect_b32 s76, s6, s7
	s_lshr_b32 s55, s56, 6
	s_lshl_b32 s57, s63, 8
	s_mov_b64 s[4:5], -1
	s_cbranch_vccnz .LBB0_536
; #define LAS __attribute__((address_space(3)))
; __device__ __forceinline__ int v_rd_base(int lane) { return ((lane & 3) << 3) | (((lane >> 2) & 3) << 6) | (((lane >> 4) & 1) << 5) | (((lane >> 5) & 1) << 8); }
; template <int NCB, bool DIFF, bool STAT>
; __device__ __forceinline__ void attn_unit(LAS char* lds, const Params& P, int s, int head, int qb, float sref) {
;     ...
;     int tid_ = threadIdx.x; asm volatile("" : "+v"(tid_));
;     const int tid = tid_, lane = tid & 63, r32 = lane & 31, hi = lane >> 5; const int wid = __builtin_amdgcn_readfirstlane(tid >> 6);
;     const int n = seq_len(s), sb = seq_base(s), NT = n >> 6, q0 = qb * 256;
;     LAS float* wsf = (LAS float*)(lds + L_WS) + wid * 64; LAS float* li_l = wsf; LAS float* al_l = wsf + 32;
;     LAS float* tab = (LAS float*)(lds + L_TAB);
;     const unsigned lds0 = (unsigned)(uintptr_t)lds;
;     const LAS char* vp0 = lds + L_V + v_rd_base(lane);
;     const LAS char* kp0 = lds + L_K + hi * 1024 + r32 * 16;
;     unsigned char* ws = P.ws;
;     f32x16 o[NCB];
;     float bL = 0.f, bR = 0.f;
;     if constexpr (DIFF) {
;         __syncthreads();
;         { const int rel = tid - 256; const int nn = rel < 0 ? -rel : rel;
;           int b = nn < 8 ? nn : (2 + (31 - __builtin_clz((unsigned)(nn * nn)))); b = b > 15 ? 15 : b; if (rel > 0) b += 16;
;           tab[tid] = P.in[4][b * 4 + head] * LOG2E; }
;         bL = P.in[4][15 * 4 + head] * LOG2E; bR = P.in[4][31 * 4 + head] * LOG2E;
;     }
;     const int qw = q0 + wid * 32;
; #pragma unroll 1
;     for (int mp = 0; mp < NMAP; ++mp) {
;         const bf16* Qw; const unsigned char* Kimg; const unsigned char* Vimg;
;         if constexpr (DIFF) {
;             Qw = (const bf16*)(ws + WS_QD) + ((size_t)sb * 8 + (size_t)(head * 2 + mp) * n + qw) * 64;
;             Kimg = ws + WS_KD + ((size_t)sb * 8 + (size_t)(head * 2 + mp) * n) * 128;
;             Vimg = ws + WS_VD + ((size_t)sb * 4 + (size_t)head * n) * 256;
;         } else {
;             Qw = (const bf16*)(ws + WS_QG) + ((size_t)sb * 8 + (size_t)head * n + qw) * 64;
;             Kimg = ws + WS_KG + ((size_t)sb * 2 + (size_t)(head >> 2) * n) * 128;
;             Vimg = ws + WS_VG + ((size_t)sb * 2 + (size_t)(head >> 2) * n) * 128;
;         }
;         const unsigned dvoff = (unsigned)(wid * 1024 + lane * 16);
;         const unsigned kdst = lds0 + L_K + wid * 1024, vdst = lds0 + L_V + wid * 1024;
	v_mov_b32_e32 v4, v230
	s_nop 0
	v_and_b32_e32 v6, 63, v4
	v_lshlrev_b32_e32 v2, 3, v6
	v_lshlrev_b32_e32 v5, 4, v6
	v_and_b32_e32 v3, 24, v2
	v_and_b32_e32 v9, 0xc0, v5
	v_lshlrev_b32_e32 v10, 1, v4
	v_and_b32_e32 v8, 31, v4
	v_bfe_u32 v7, v4, 5, 1
	v_and_b32_e32 v10, 32, v10
	v_and_b32_e32 v2, 0x100, v2
	v_add3_u32 v3, 0, v3, v9
	v_add3_u32 v204, v3, v10, v2
	v_lshlrev_b32_e32 v2, 10, v7
	v_lshlrev_b32_e32 v3, 4, v8
	v_add3_u32 v205, s65, v2, v3
	v_add_u32_e32 v2, 0xffffff00, v4
	v_cmp_gt_i32_e32 vcc, s33, v4
	v_sub_u32_e32 v3, 0x100, v4
	s_barrier
	v_cndmask_b32_e32 v2, v2, v3, vcc
	v_mul_lo_u32 v3, v2, v2
	v_ffbh_u32_e32 v3, v3
	v_sub_u32_e32 v3, 33, v3
	v_cmp_gt_i32_e32 vcc, 8, v2
	v_min_u32_e32 v3, 15, v3
	s_nop 0
	v_cndmask_b32_e32 v2, v3, v2, vcc
	v_lshlrev_b32_e32 v2, 2, v2
	v_cmp_lt_i32_e32 vcc, s33, v4
	v_add_u32_e32 v3, 64, v2
	v_readfirstlane_b32 s4, v4
	v_cndmask_b32_e32 v2, v2, v3, vcc
	v_ashrrev_i32_e32 v3, 31, v2
	v_lshl_add_u64 v[2:3], v[2:3], 2, s[74:75]
	global_load_dword v2, v[2:3], off
	v_lshl_add_u32 v3, v4, 2, s68
	s_ashr_i32 s8, s4, 6
	s_and_b32 s4, s4, 0x3fffffc0
	s_lshl_b32 s4, s4, 2
	s_add_i32 s46, s4, 0
	s_lshl_b32 s4, s8, 5
	s_mov_b32 s77, s15
	s_add_i32 s46, s46, 0x1e000
	s_add_i32 s58, s4, s57
	s_lshl_b64 s[80:81], s[76:77], 3
	s_and_b64 s[4:5], s[78:79], exec
	s_cselect_b32 s59, 14, 12
	s_lshl_b64 s[4:5], s[72:73], s59
	s_ashr_i32 s60, s58, 31
	s_lshl_b64 s[40:41], s[76:77], 10
	s_lshl_b64 s[42:43], s[4:5], 8
	s_add_u32 s4, s61, s40
	s_addc_u32 s5, s66, s41
	s_add_u32 s82, s4, s42
	s_mov_b32 s1, s0
	s_mov_b32 s0, s61
	s_addc_u32 s83, s5, s43
	s_lshl_b32 s61, s8, 10
	v_or_b32_e32 v208, s61, v5
	s_add_i32 s77, s61, s65
	s_add_i32 s61, s61, 0
	s_add_u32 s84, s82, 0x2000
	s_addc_u32 s85, s83, 0
	s_add_u32 s86, s82, 0x4000
	s_addc_u32 s87, s83, 0
	s_add_u32 s88, s82, 0x6000
	s_addc_u32 s89, s83, 0
	s_add_u32 s90, s82, 0x8000
	s_addc_u32 s91, s83, 0
	s_add_u32 s92, s82, 0xa000
	s_addc_u32 s93, s83, 0
	s_add_i32 s69, s14, 0xed8
	v_readlane_b32 s4, v254, 43
	s_cmpk_gt_i32 s58, 0xbe
	v_readlane_b32 s5, v254, 44
	s_cselect_b64 vcc, -1, 0
	s_cmpk_lt_i32 s58, 0xff62
	v_lshlrev_b32_e32 v4, 4, v7
	v_mov_b32_e32 v5, v0
	s_mov_b64 s[12:13], s[34:35]
	v_mov_b32_e32 v9, v0
	v_readlane_b32 s16, v254, 1
	v_readlane_b32 s30, v254, 15
	v_readlane_b32 s31, v254, 16
	s_mov_b32 s9, 0
	s_mov_b32 s33, s66
	v_add_u32_e32 v214, s46, v4
	v_readlane_b32 s17, v254, 2
	v_readlane_b32 s18, v254, 3
	v_readlane_b32 s19, v254, 4
	v_readlane_b32 s20, v254, 5
	v_readlane_b32 s21, v254, 6
	v_readlane_b32 s22, v254, 7
	v_readlane_b32 s23, v254, 8
	v_readlane_b32 s24, v254, 9
	v_readlane_b32 s25, v254, 10
	v_readlane_b32 s26, v254, 11
	v_readlane_b32 s27, v254, 12
	v_readlane_b32 s28, v254, 13
	v_readlane_b32 s29, v254, 14
	s_waitcnt vmcnt(0)
	v_mul_f32_e32 v2, 0x3fb8aa3b, v2
	ds_write_b32 v3, v2
	global_load_dword v2, v0, s[74:75] offset:240
	v_mov_b32_e32 v3, v0
	s_waitcnt vmcnt(0)
	v_mul_f32_e32 v206, 0x3fb8aa3b, v2
	global_load_dword v2, v0, s[74:75] offset:496
	s_waitcnt vmcnt(0)
	v_mul_f32_e32 v207, 0x3fb8aa3b, v2
	v_lshlrev_b32_e32 v2, 7, v8
	v_lshl_add_u64 v[2:3], s[4:5], 0, v[2:3]
	s_cselect_b64 s[4:5], -1, 0
	v_lshl_add_u64 v[170:171], v[2:3], 0, v[4:5]
	v_cndmask_b32_e64 v2, 0, v207, s[4:5]
	s_add_i32 s4, s58, 0x9e
	s_cmpk_lt_u32 s4, 0x15d
	s_cselect_b64 s[94:95], -1, 0
	s_sub_i32 s6, s56, s58
	v_cndmask_b32_e32 v2, v2, v206, vcc
	s_sub_i32 s7, s6, 64
	v_cmp_neq_f32_e32 vcc, 0, v2
	s_cmpk_lt_i32 s7, 0xff42
	v_lshlrev_b32_e32 v3, 2, v7
	v_cndmask_b32_e32 v209, 0, v2, vcc
	s_cselect_b64 vcc, -1, 0
	s_cmpk_gt_i32 s7, 0x9e
	s_cselect_b64 s[4:5], -1, 0
	s_addk_i32 s6, 0x7e
	s_cmpk_lt_u32 s6, 0x15d
	v_cndmask_b32_e64 v2, 0, v207, s[4:5]
	s_cselect_b64 s[96:97], -1, 0
	s_add_i32 s4, s58, s76
	s_ashr_i32 s5, s4, 31
	s_lshl_b64 s[4:5], s[4:5], 11
	s_add_u32 s4, s12, s4
	v_cndmask_b32_e32 v211, v2, v206, vcc
	v_sub_u32_e32 v2, s7, v8
	v_cmp_gt_u32_e64 s[6:7], 32, v6
	s_addc_u32 s5, s13, s5
	v_lshlrev_b32_e32 v6, 13, v7
	v_mov_b32_e32 v7, v0
	v_lshlrev_b32_e32 v2, 2, v2
	v_lshl_add_u64 v[6:7], s[4:5], 0, v[6:7]
	s_lshl_b32 s14, s72, 8
	v_or_b32_e32 v5, s58, v8
	v_add3_u32 v212, s68, v2, v4
	v_lshlrev_b32_e32 v2, 2, v8
	v_lshl_add_u64 v[6:7], v[6:7], 0, s[14:15]
	v_lshlrev_b32_e32 v8, 1, v8
	v_lshl_add_u64 v[172:173], v[6:7], 0, v[8:9]
	s_mov_b64 s[4:5], 0x1400
	v_lshl_add_u64 v[174:175], v[172:173], 0, s[4:5]
	s_mov_b64 s[4:5], 0x1c00
	v_lshl_add_u64 v[176:177], v[172:173], 0, s[4:5]
	s_mov_b64 s[4:5], 0x4400
	v_lshl_add_u64 v[178:179], v[172:173], 0, s[4:5]
	s_mov_b64 s[4:5], 0x4c00
	v_lshl_add_u64 v[180:181], v[172:173], 0, s[4:5]
	s_mov_b64 s[4:5], 0x5400
	v_lshl_add_u64 v[182:183], v[172:173], 0, s[4:5]
	s_mov_b64 s[4:5], 0x5c00
	v_lshl_add_u64 v[184:185], v[172:173], 0, s[4:5]
	s_mov_b64 s[4:5], 0x8400
	v_lshl_add_u64 v[186:187], v[172:173], 0, s[4:5]
	s_mov_b64 s[4:5], 0x8c00
	v_lshl_add_u64 v[188:189], v[172:173], 0, s[4:5]
	s_mov_b64 s[4:5], 0x9400
	v_lshl_add_u64 v[190:191], v[172:173], 0, s[4:5]
	s_mov_b64 s[4:5], 0x9c00
	v_lshl_add_u64 v[192:193], v[172:173], 0, s[4:5]
	s_mov_b64 s[4:5], 0xc400
	v_lshl_add_u64 v[194:195], v[172:173], 0, s[4:5]
	s_mov_b64 s[4:5], 0xcc00
	v_sub_u32_e32 v3, v3, v5
	v_lshl_add_u64 v[196:197], v[172:173], 0, s[4:5]
	s_mov_b64 s[4:5], 0xd400
	v_lshl_add_u32 v210, v3, 2, s68
	v_lshl_add_u64 v[198:199], v[172:173], 0, s[4:5]
	s_mov_b64 s[4:5], 0xdc00
	v_mov_b32_e32 v3, v0
	v_add_u32_e32 v213, s46, v2
	v_lshl_add_u64 v[200:201], v[172:173], 0, s[4:5]
	v_lshl_add_u64 v[202:203], s[30:31], 0, v[2:3]
	v_sub_u32_e32 v2, v4, v2
	s_lshl_b32 s4, s8, 7
	v_subrev_u32_e32 v2, s4, v2
	s_lshl_b32 s4, s63, 10
	v_subrev_u32_e32 v2, s4, v2
	v_readlane_b32 s4, v254, 53
	s_sub_i32 s8, 0x13e, s58
	v_readlane_b32 s12, v254, 51
	v_add_u32_e32 v215, s4, v2
	s_add_u32 s4, s40, s42
	s_addc_u32 s5, s41, s43
	s_add_u32 s48, s12, s4
	v_readlane_b32 s4, v254, 52
	s_addc_u32 s49, s4, s5
	s_mov_b64 s[46:47], -1
	s_branch .LBB0_509

; #define LAS __attribute__((address_space(3)))
; #define PKW(P, B) cvtpk(P[B], P[B + 1])
; #define MFMA32(a, b, c) __builtin_amdgcn_mfma_f32_32x32x16_bf16(a, b, c, 0, 0, 0)
; #define VRD(g) do { const int o_ = ((g) % NCB) * 512 + (2 * ((g) / NCB)) * NCB * 512; vl[(g) % 3] = tr_rd(vp_ + o_); vh[(g) % 3] = tr_rd(vp_ + o_ + NCB * 512); } while (0)
; template <int NCB, bool DIFF, bool STAT>
; __device__ __forceinline__ void attn_unit(LAS char* lds, const Params& P, int s, int head, int qb, float sref) {
;     ...
;         for (int j = 1; j + 1 < NT; j += 2) {
;             STEP(pB0, pB1, alB, pA0, pA1, alA, j, false, false);
;             STEP(pA0, pA1, alA, pB0, pB1, alB, j + 1, true, true);
;         }
;         STEP(pB0, pB1, alB, pA0, pA1, alA, NT - 1, false, false);
;         { const LAS char* vp_ = vp0 + sl_prev * SHM_V; s16x4 vl[3], vh[3];
;           float s0_ = 0.f;
; #pragma unroll
;           for (int r = 0; r < 16; ++r) s0_ += pB0[r] + pB1[r];
;           if constexpr (STAT) l_reg += s0_; else l_reg = l_reg * alB + s0_;
;           pw[0] = (u32x4){PKW(pB0, 0), PKW(pB0, 2), PKW(pB0, 4), PKW(pB0, 6)}; pw[1] = (u32x4){PKW(pB0, 8), PKW(pB0, 10), PKW(pB0, 12), PKW(pB0, 14)};
;           pw[2] = (u32x4){PKW(pB1, 0), PKW(pB1, 2), PKW(pB1, 4), PKW(pB1, 6)}; pw[3] = (u32x4){PKW(pB1, 8), PKW(pB1, 10), PKW(pB1, 12), PKW(pB1, 14)};
; #pragma unroll
;           for (int g = 0; g < NG; ++g) { VRD(g); o[g % NCB] = MFMA32(__builtin_bit_cast(bf16x8, pw[g / NCB]), PKV(vl[g % 3], vh[g % 3]), o[g % NCB]); } }
.LBB0_529:
	s_waitcnt lgkmcnt(2)
	v_mfma_f32_32x32x16_bf16 v[50:65], v[130:133], v[90:93], v[50:65]
	ds_read_b64_tr_b16 v[106:107], v134 offset:1024
	ds_read_b64_tr_b16 v[108:109], v134 offset:3072
	v_add_f32_e32 v94, v94, v95
	v_exp_f32_e32 v114, v114
	v_exp_f32_e32 v115, v115
	v_add_f32_e32 v94, v216, v94
	s_waitcnt lgkmcnt(2)
	v_mfma_f32_32x32x16_bf16 v[66:81], v[130:133], v[86:89], v[66:81]
	ds_read_b64_tr_b16 v[90:91], v134 offset:1536
	ds_read_b64_tr_b16 v[92:93], v134 offset:3584
	v_exp_f32_e32 v116, v116
	v_exp_f32_e32 v117, v117
	s_waitcnt lgkmcnt(2)
	v_mfma_f32_32x32x16_bf16 v[2:17], v[130:133], v[106:109], v[2:17]
	ds_read_b64_tr_b16 v[86:87], v134 offset:4096
	ds_read_b64_tr_b16 v[88:89], v134 offset:6144
	v_exp_f32_e32 v118, v118
	v_exp_f32_e32 v119, v119
	s_waitcnt lgkmcnt(2)
	v_mfma_f32_32x32x16_bf16 v[18:33], v[130:133], v[90:93], v[18:33]
	ds_read_b64_tr_b16 v[106:107], v134 offset:4608
	ds_read_b64_tr_b16 v[108:109], v134 offset:6656
	v_exp_f32_e32 v120, v120
	v_exp_f32_e32 v121, v121
	s_waitcnt lgkmcnt(2)
	v_mfma_f32_32x32x16_bf16 v[50:65], v[102:105], v[86:89], v[50:65]
	ds_read_b64_tr_b16 v[90:91], v134 offset:5120
	ds_read_b64_tr_b16 v[92:93], v134 offset:7168
	v_exp_f32_e32 v122, v122
	v_exp_f32_e32 v123, v123
	s_waitcnt lgkmcnt(2)
	v_mfma_f32_32x32x16_bf16 v[66:81], v[102:105], v[106:109], v[66:81]
	ds_read_b64_tr_b16 v[86:87], v134 offset:5632
	ds_read_b64_tr_b16 v[88:89], v134 offset:7680
	v_exp_f32_e32 v124, v124
	v_exp_f32_e32 v125, v125
	s_waitcnt lgkmcnt(2)
	v_mfma_f32_32x32x16_bf16 v[2:17], v[102:105], v[90:93], v[2:17]
	ds_read_b64_tr_b16 v[106:107], v134 offset:8192
	ds_read_b64_tr_b16 v[108:109], v134 offset:10240
	v_exp_f32_e32 v126, v126
	v_exp_f32_e32 v127, v127
	s_waitcnt lgkmcnt(2)
	v_mfma_f32_32x32x16_bf16 v[18:33], v[102:105], v[86:89], v[18:33]
	ds_read_b64_tr_b16 v[90:91], v134 offset:8704
	ds_read_b64_tr_b16 v[92:93], v134 offset:10752
	v_exp_f32_e32 v128, v128
	v_exp_f32_e32 v129, v129
	s_waitcnt lgkmcnt(2)
	v_mfma_f32_32x32x16_bf16 v[50:65], v[98:101], v[106:109], v[50:65]
	ds_read_b64_tr_b16 v[86:87], v134 offset:9216
	ds_read_b64_tr_b16 v[88:89], v134 offset:11264
	v_exp_f32_e32 v34, v34
	v_exp_f32_e32 v35, v35
	s_waitcnt lgkmcnt(2)
	v_mfma_f32_32x32x16_bf16 v[66:81], v[98:101], v[90:93], v[66:81]
	ds_read_b64_tr_b16 v[102:103], v134 offset:9728
	ds_read_b64_tr_b16 v[104:105], v134 offset:11776
	v_exp_f32_e32 v36, v36
	v_exp_f32_e32 v37, v37
	s_waitcnt lgkmcnt(2)
	v_mfma_f32_32x32x16_bf16 v[2:17], v[98:101], v[86:89], v[2:17]
	ds_read_b64_tr_b16 v[90:91], v134 offset:12288
	ds_read_b64_tr_b16 v[92:93], v134 offset:14336
	v_exp_f32_e32 v38, v38
	v_exp_f32_e32 v39, v39
	s_waitcnt lgkmcnt(2)
	v_mfma_f32_32x32x16_bf16 v[18:33], v[98:101], v[102:105], v[18:33]
	ds_read_b64_tr_b16 v[86:87], v134 offset:12800
	ds_read_b64_tr_b16 v[88:89], v134 offset:14848
	v_exp_f32_e32 v40, v40
	v_exp_f32_e32 v41, v41
	s_waitcnt lgkmcnt(2)
	v_mfma_f32_32x32x16_bf16 v[50:65], v[82:85], v[90:93], v[50:65]
	ds_read_b64_tr_b16 v[96:97], v134 offset:13312
	ds_read_b64_tr_b16 v[98:99], v134 offset:15360
	v_exp_f32_e32 v42, v42
	v_exp_f32_e32 v43, v43
	s_waitcnt lgkmcnt(2)
	v_mfma_f32_32x32x16_bf16 v[66:81], v[82:85], v[86:89], v[66:81]
	ds_read_b64_tr_b16 v[90:91], v134 offset:13824
	ds_read_b64_tr_b16 v[92:93], v134 offset:15872
	v_exp_f32_e32 v44, v44
	v_exp_f32_e32 v45, v45
	s_waitcnt lgkmcnt(2)
	v_mfma_f32_32x32x16_bf16 v[2:17], v[82:85], v[96:99], v[2:17]
	v_exp_f32_e32 v46, v46
	v_exp_f32_e32 v47, v47
	s_waitcnt lgkmcnt(0)
	v_mfma_f32_32x32x16_bf16 v[18:33], v[82:85], v[90:93], v[18:33]
	v_exp_f32_e32 v48, v48
	v_exp_f32_e32 v49, v49
	v_lshl_add_u32 v111, s14, 14, v204
	v_add_f32_e32 v95, v114, v34
	v_add_f32_e32 v96, v115, v35
	v_add_f32_e32 v97, v116, v36
	v_add_f32_e32 v98, v117, v37
	v_add_f32_e32 v99, v118, v38
	v_add_f32_e32 v100, v119, v39
	v_add_f32_e32 v101, v120, v40
	v_add_f32_e32 v102, v121, v41
	v_cvt_pk_bf16_f32 v82, v114, v115
	v_cvt_pk_bf16_f32 v83, v116, v117
	v_cvt_pk_bf16_f32 v84, v118, v119
	v_cvt_pk_bf16_f32 v85, v120, v121
	v_cvt_pk_bf16_f32 v86, v122, v123
	v_cvt_pk_bf16_f32 v87, v124, v125
	v_cvt_pk_bf16_f32 v88, v126, v127
	v_cvt_pk_bf16_f32 v89, v128, v129
	v_cvt_pk_bf16_f32 v90, v34, v35
	v_cvt_pk_bf16_f32 v91, v36, v37
	v_cvt_pk_bf16_f32 v92, v38, v39
	v_cvt_pk_bf16_f32 v93, v40, v41
	v_cvt_pk_bf16_f32 v34, v42, v43
	v_cvt_pk_bf16_f32 v35, v44, v45
	v_cvt_pk_bf16_f32 v36, v46, v47
	v_cvt_pk_bf16_f32 v37, v48, v49
	ds_read_b64_tr_b16 v[38:39], v111
	ds_read_b64_tr_b16 v[40:41], v111 offset:2048
	s_waitcnt lgkmcnt(0)
	v_mfma_f32_32x32x16_bf16 v[50:65], v[82:85], v[38:41], v[50:65]
	ds_read_b64_tr_b16 v[38:39], v111 offset:512
	ds_read_b64_tr_b16 v[40:41], v111 offset:2560
	v_add_f32_e32 v103, v122, v42
	v_add_f32_e32 v104, v123, v43
	v_add_f32_e32 v105, v124, v44
	v_add_f32_e32 v106, v125, v45
	v_add_f32_e32 v107, v126, v46
	v_add_f32_e32 v108, v127, v47
	s_waitcnt lgkmcnt(0)
	v_mfma_f32_32x32x16_bf16 v[66:81], v[82:85], v[38:41], v[66:81]
	ds_read_b64_tr_b16 v[38:39], v111 offset:1024
	ds_read_b64_tr_b16 v[40:41], v111 offset:3072
	v_add_f32_e32 v109, v128, v48
	v_add_f32_e32 v110, v129, v49
	s_waitcnt lgkmcnt(0)
	v_mfma_f32_32x32x16_bf16 v[2:17], v[82:85], v[38:41], v[2:17]
	ds_read_b64_tr_b16 v[38:39], v111 offset:1536
	ds_read_b64_tr_b16 v[40:41], v111 offset:3584
	s_waitcnt lgkmcnt(0)
	v_mfma_f32_32x32x16_bf16 v[18:33], v[82:85], v[38:41], v[18:33]
	ds_read_b64_tr_b16 v[38:39], v111 offset:4096
	ds_read_b64_tr_b16 v[40:41], v111 offset:6144
	s_waitcnt lgkmcnt(0)
	v_mfma_f32_32x32x16_bf16 v[50:65], v[86:89], v[38:41], v[50:65]
	ds_read_b64_tr_b16 v[38:39], v111 offset:4608
	ds_read_b64_tr_b16 v[40:41], v111 offset:6656
	s_waitcnt lgkmcnt(0)
; __device__ __forceinline__ int crow(int r, int hi) { return (r & 3) + 8 * (r >> 2) + 4 * hi; }
; __device__ __forceinline__ int crow(int r, int hi) { return (r & 3) + 8 * (r >> 2) + 4 * hi; }
; #define MFMA32(a, b, c) __builtin_amdgcn_mfma_f32_32x32x16_bf16(a, b, c, 0, 0, 0)
; #define VRD(g) do { const int o_ = ((g) % NCB) * 512 + (2 * ((g) / NCB)) * NCB * 512; vl[(g) % 3] = tr_rd(vp_ + o_); vh[(g) % 3] = tr_rd(vp_ + o_ + NCB * 512); } while (0)
; template <int NCB, bool DIFF, bool STAT>
; __device__ __forceinline__ void attn_unit(LAS char* lds, const Params& P, int s, int head, int qb, float sref) {
;     ...
;           for (int g = 0; g < NG; ++g) { VRD(g); o[g % NCB] = MFMA32(__builtin_bit_cast(bf16x8, pw[g / NCB]), PKV(vl[g % 3], vh[g % 3]), o[g % NCB]); } }
;     ...
;         { auto rr = __builtin_amdgcn_permlane32_swap(__float_as_uint(l_reg), __float_as_uint(l_reg), false, false); l_reg = __uint_as_float(rr[0]) + __uint_as_float(rr[1]); }
;         if (hi == 0) li_l[r32] = l_reg; asm volatile("s_waitcnt lgkmcnt(0)" ::: "memory");
;         float rli[16];
; #pragma unroll
;         for (int r = 0; r < 16; ++r) rli[r] = __builtin_amdgcn_rcpf(li_l[crow(r, hi)]);
	v_mfma_f32_32x32x16_bf16 v[66:81], v[86:89], v[38:41], v[66:81]
	ds_read_b64_tr_b16 v[38:39], v111 offset:5120
	ds_read_b64_tr_b16 v[40:41], v111 offset:7168
	s_waitcnt lgkmcnt(0)
	v_mfma_f32_32x32x16_bf16 v[2:17], v[86:89], v[38:41], v[2:17]
	ds_read_b64_tr_b16 v[38:39], v111 offset:5632
	ds_read_b64_tr_b16 v[40:41], v111 offset:7680
	s_waitcnt lgkmcnt(0)
	v_mfma_f32_32x32x16_bf16 v[18:33], v[86:89], v[38:41], v[18:33]
	ds_read_b64_tr_b16 v[38:39], v111 offset:8192
	ds_read_b64_tr_b16 v[40:41], v111 offset:10240
	s_waitcnt lgkmcnt(0)
	v_mfma_f32_32x32x16_bf16 v[50:65], v[90:93], v[38:41], v[50:65]
	ds_read_b64_tr_b16 v[38:39], v111 offset:8704
	ds_read_b64_tr_b16 v[40:41], v111 offset:10752
	s_waitcnt lgkmcnt(0)
	v_mfma_f32_32x32x16_bf16 v[66:81], v[90:93], v[38:41], v[66:81]
	ds_read_b64_tr_b16 v[38:39], v111 offset:9216
	ds_read_b64_tr_b16 v[40:41], v111 offset:11264
	s_waitcnt lgkmcnt(0)
	v_mfma_f32_32x32x16_bf16 v[2:17], v[90:93], v[38:41], v[2:17]
	ds_read_b64_tr_b16 v[38:39], v111 offset:9728
	ds_read_b64_tr_b16 v[40:41], v111 offset:11776
	s_waitcnt lgkmcnt(0)
	v_mfma_f32_32x32x16_bf16 v[18:33], v[90:93], v[38:41], v[18:33]
	ds_read_b64_tr_b16 v[38:39], v111 offset:12288
	ds_read_b64_tr_b16 v[40:41], v111 offset:14336
	s_waitcnt lgkmcnt(0)
	v_mfma_f32_32x32x16_bf16 v[50:65], v[34:37], v[38:41], v[50:65]
	ds_read_b64_tr_b16 v[38:39], v111 offset:12800
	ds_read_b64_tr_b16 v[40:41], v111 offset:14848
	s_waitcnt lgkmcnt(0)
	v_mfma_f32_32x32x16_bf16 v[66:81], v[34:37], v[38:41], v[66:81]
	ds_read_b64_tr_b16 v[38:39], v111 offset:13312
	ds_read_b64_tr_b16 v[40:41], v111 offset:15360
	s_waitcnt lgkmcnt(0)
	v_mfma_f32_32x32x16_bf16 v[2:17], v[34:37], v[38:41], v[2:17]
	ds_read_b64_tr_b16 v[38:39], v111 offset:13824
	ds_read_b64_tr_b16 v[40:41], v111 offset:15872
	s_waitcnt lgkmcnt(0)
	v_mfma_f32_32x32x16_bf16 v[18:33], v[34:37], v[38:41], v[18:33]
	v_add_f32_e32 v34, 0, v95
	v_add_f32_e32 v34, v96, v34
	v_add_f32_e32 v34, v97, v34
	v_add_f32_e32 v34, v98, v34
	v_add_f32_e32 v34, v99, v34
	v_add_f32_e32 v34, v100, v34
	v_add_f32_e32 v34, v101, v34
	v_add_f32_e32 v34, v102, v34
	v_add_f32_e32 v34, v103, v34
	v_add_f32_e32 v34, v104, v34
	v_add_f32_e32 v34, v105, v34
	v_add_f32_e32 v34, v106, v34
	v_add_f32_e32 v34, v107, v34
	v_add_f32_e32 v34, v108, v34
	v_add_f32_e32 v34, v109, v34
	v_add_f32_e32 v34, v110, v34
	v_add_f32_e32 v34, v94, v34
	v_mov_b32_e32 v35, v34
	s_nop 1
	v_permlane32_swap_b32_e32 v34, v35
	s_and_saveexec_b64 s[4:5], s[6:7]
	v_add_f32_e32 v34, v34, v35
	ds_write_b32 v213, v34
	s_or_b64 exec, exec, s[4:5]
	s_waitcnt lgkmcnt(0)
	ds_read_b128 v[34:37], v214
	ds_read_b128 v[38:41], v214 offset:32
	s_mov_b64 s[4:5], -1
	s_and_b64 vcc, exec, s[42:43]
	s_waitcnt lgkmcnt(1)
	v_rcp_f32_e32 v89, v34
	v_rcp_f32_e32 v90, v35
	v_rcp_f32_e32 v91, v36
	v_rcp_f32_e32 v92, v37
	s_waitcnt lgkmcnt(0)
	v_rcp_f32_e32 v93, v38
	ds_read_b128 v[34:37], v214 offset:64
	v_rcp_f32_e32 v94, v39
	v_rcp_f32_e32 v95, v40
	v_rcp_f32_e32 v96, v41
	ds_read_b128 v[38:41], v214 offset:96
	s_waitcnt lgkmcnt(1)
	v_rcp_f32_e32 v97, v34
	v_rcp_f32_e32 v98, v35
	v_rcp_f32_e32 v99, v36
	v_rcp_f32_e32 v100, v37
	s_waitcnt lgkmcnt(0)
	v_rcp_f32_e32 v101, v38
	v_rcp_f32_e32 v102, v39
	v_rcp_f32_e32 v103, v40
	v_rcp_f32_e32 v34, v41
	v_mul_f32_e32 v87, v50, v89
	v_mul_f32_e32 v86, v51, v90
	v_mul_f32_e32 v85, v52, v91
	v_mul_f32_e32 v84, v53, v92
	v_mul_f32_e32 v83, v54, v93
	v_mul_f32_e32 v82, v55, v94
	v_mul_f32_e32 v53, v56, v95
	v_mul_f32_e32 v50, v57, v96
	v_mul_f32_e32 v48, v58, v97
	v_mul_f32_e32 v46, v59, v98
	v_mul_f32_e32 v44, v60, v99
	v_mul_f32_e32 v42, v61, v100
	v_mul_f32_e32 v40, v62, v101
	v_mul_f32_e32 v38, v63, v102
	v_mul_f32_e32 v36, v64, v103
	v_mul_f32_e32 v35, v65, v34
	v_mul_f32_e32 v88, v66, v89
	v_mul_f32_e32 v66, v67, v90
	v_mul_f32_e32 v64, v68, v91
	v_mul_f32_e32 v62, v69, v92
	v_mul_f32_e32 v60, v70, v93
	v_mul_f32_e32 v58, v71, v94
	v_mul_f32_e32 v56, v72, v95
	v_mul_f32_e32 v54, v73, v96
	v_mul_f32_e32 v51, v74, v97
	v_mul_f32_e32 v49, v75, v98
	v_mul_f32_e32 v47, v76, v99
	v_mul_f32_e32 v45, v77, v100
	v_mul_f32_e32 v43, v78, v101
	v_mul_f32_e32 v41, v79, v102
	v_mul_f32_e32 v39, v80, v103
	v_mul_f32_e32 v37, v81, v34
	v_mul_f32_e32 v70, v2, v89
	v_mul_f32_e32 v68, v3, v90
	v_mul_f32_e32 v67, v4, v91
	v_mul_f32_e32 v65, v5, v92
	v_mul_f32_e32 v63, v6, v93
	v_mul_f32_e32 v61, v7, v94
	v_mul_f32_e32 v59, v8, v95
	v_mul_f32_e32 v57, v9, v96
	v_mul_f32_e32 v55, v10, v97
	v_mul_f32_e32 v52, v11, v98
	v_mul_f32_e32 v11, v12, v99
	v_mul_f32_e32 v9, v13, v100
	v_mul_f32_e32 v7, v14, v101
	v_mul_f32_e32 v5, v15, v102
	v_mul_f32_e32 v4, v16, v103
	v_mul_f32_e32 v72, v18, v89
	v_mul_f32_e32 v71, v19, v90
	v_mul_f32_e32 v69, v20, v91
	v_mul_f32_e32 v21, v21, v92
	v_mul_f32_e32 v20, v22, v93
	v_mul_f32_e32 v19, v23, v94
	v_mul_f32_e32 v18, v24, v95
	v_mul_f32_e32 v16, v25, v96
	v_mul_f32_e32 v15, v26, v97
	v_mul_f32_e32 v14, v27, v98
	v_mul_f32_e32 v13, v28, v99
	v_mul_f32_e32 v12, v29, v100
	v_mul_f32_e32 v10, v30, v101
	v_mul_f32_e32 v8, v31, v102
	v_mul_f32_e32 v6, v32, v103
	s_cbranch_vccz .LBB0_533
; __device__ __forceinline__ int crow(int r, int hi) { return (r & 3) + 8 * (r >> 2) + 4 * hi; }
; __device__ __forceinline__ int crow(int r, int hi) { return (r & 3) + 8 * (r >> 2) + 4 * hi; }
; template <int NCB, bool DIFF, bool STAT>
; __device__ __forceinline__ void attn_unit(LAS char* lds, const Params& P, int s, int head, int qb, float sref) {
;     ...
;                 const float lam = *(const float*)(ws + WS_LAM);
;                 float ss[16];
; #pragma unroll
;                 for (int r = 0; r < 16; ++r) ss[r] = 0.f;
; #pragma unroll
;                 for (int d0 = 0; d0 < NCB; ++d0)
; #pragma unroll
;                     for (int r = 0; r < 16; ++r) { const float o1 = bf2f(mixw[(size_t)crow(r, hi) * DM + 512 + head * 128 + d0 * 32 + r32]);
;                         const float a0 = o1 - lam * (o[d0][r] * rli[r]); o[d0][r] = a0; ss[r] += a0 * a0; }
	global_load_dword v2, v0, s[10:11]
	global_load_ushort v150, v[172:173], off offset:1024
	global_load_ushort v151, v[172:173], off offset:3072
	global_load_ushort v152, v[174:175], off
	global_load_ushort v153, v[176:177], off
	global_load_ushort v154, v[178:179], off
	global_load_ushort v155, v[180:181], off
	global_load_ushort v156, v[182:183], off
	global_load_ushort v157, v[184:185], off
	global_load_ushort v158, v[186:187], off
	global_load_ushort v159, v[188:189], off
	global_load_ushort v160, v[190:191], off
	global_load_ushort v161, v[192:193], off
	global_load_ushort v162, v[194:195], off
	global_load_ushort v163, v[196:197], off
	global_load_ushort v164, v[198:199], off
	global_load_ushort v165, v[200:201], off
	global_load_ushort v166, v[172:173], off offset:1088
	global_load_ushort v167, v[172:173], off offset:3136
	global_load_ushort v168, v[174:175], off offset:64
	global_load_ushort v169, v[176:177], off offset:64
	global_load_ushort v216, v[178:179], off offset:64
	global_load_ushort v218, v[180:181], off offset:64
	global_load_ushort v219, v[182:183], off offset:64
	global_load_ushort v220, v[184:185], off offset:64
	global_load_ushort v221, v[186:187], off offset:64
	global_load_ushort v222, v[188:189], off offset:64
	global_load_ushort v223, v[190:191], off offset:64
	global_load_ushort v224, v[192:193], off offset:64
	global_load_ushort v225, v[194:195], off offset:64
	global_load_ushort v226, v[196:197], off offset:64
	global_load_ushort v227, v[198:199], off offset:64
	global_load_ushort v228, v[200:201], off offset:64
	global_load_ushort v229, v[172:173], off offset:1152
	global_load_ushort v236, v[172:173], off offset:3200
	global_load_ushort v237, v[174:175], off offset:128
	global_load_ushort v238, v[176:177], off offset:128
	global_load_ushort v239, v[178:179], off offset:128
	global_load_ushort v240, v[180:181], off offset:128
	global_load_ushort v241, v[182:183], off offset:128
	global_load_ushort v242, v[184:185], off offset:128
	global_load_ushort v243, v[186:187], off offset:128
	global_load_ushort v244, v[188:189], off offset:128
	global_load_ushort v245, v[190:191], off offset:128
	global_load_ushort v246, v[192:193], off offset:128
	global_load_ushort v247, v[194:195], off offset:128
	global_load_ushort v248, v[196:197], off offset:128
	global_load_ushort v249, v[198:199], off offset:128
	global_load_ushort v250, v[200:201], off offset:128
	global_load_ushort v251, v[172:173], off offset:1216
	global_load_ushort v252, v[172:173], off offset:3264
	global_load_ushort v253, v[174:175], off offset:192
	s_mov_b64 s[4:5], 0
	s_waitcnt vmcnt(50)
	v_lshlrev_b32_e32 v150, 16, v150
	v_fma_f32 v78, -v87, v2, v150
	s_waitcnt vmcnt(49)
	v_lshlrev_b32_e32 v151, 16, v151
	v_fma_f32 v77, -v86, v2, v151
	s_waitcnt vmcnt(48)
	v_lshlrev_b32_e32 v152, 16, v152
	v_fma_f32 v76, -v85, v2, v152
	s_waitcnt vmcnt(47)
	v_lshlrev_b32_e32 v153, 16, v153
	v_fma_f32 v75, -v84, v2, v153
	s_waitcnt vmcnt(46)
	v_lshlrev_b32_e32 v154, 16, v154
	v_fma_f32 v74, -v83, v2, v154
	s_waitcnt vmcnt(45)
	v_lshlrev_b32_e32 v155, 16, v155
	v_fma_f32 v73, -v82, v2, v155
	s_waitcnt vmcnt(44)
	v_lshlrev_b32_e32 v156, 16, v156
	v_fma_f32 v31, -v53, v2, v156
	s_waitcnt vmcnt(43)
	v_lshlrev_b32_e32 v157, 16, v157
	v_fma_f32 v30, -v50, v2, v157
	s_waitcnt vmcnt(42)
	v_lshlrev_b32_e32 v158, 16, v158
	v_fma_f32 v29, -v48, v2, v158
	s_waitcnt vmcnt(41)
	v_lshlrev_b32_e32 v159, 16, v159
	v_fma_f32 v28, -v46, v2, v159
	s_waitcnt vmcnt(40)
	v_lshlrev_b32_e32 v160, 16, v160
	v_fma_f32 v27, -v44, v2, v160
	s_waitcnt vmcnt(39)
	v_lshlrev_b32_e32 v161, 16, v161
	v_fma_f32 v26, -v42, v2, v161
	s_waitcnt vmcnt(38)
	v_lshlrev_b32_e32 v162, 16, v162
	v_fma_f32 v25, -v40, v2, v162
	global_load_ushort v150, v[176:177], off offset:192
	global_load_ushort v151, v[178:179], off offset:192
	global_load_ushort v152, v[180:181], off offset:192
	global_load_ushort v153, v[182:183], off offset:192
	global_load_ushort v154, v[184:185], off offset:192
	global_load_ushort v155, v[186:187], off offset:192
	global_load_ushort v156, v[188:189], off offset:192
	global_load_ushort v157, v[190:191], off offset:192
	global_load_ushort v158, v[192:193], off offset:192
	global_load_ushort v159, v[194:195], off offset:192
	global_load_ushort v160, v[196:197], off offset:192
	global_load_ushort v161, v[198:199], off offset:192
	global_load_ushort v162, v[200:201], off offset:192
	s_waitcnt vmcnt(50)
	v_lshlrev_b32_e32 v163, 16, v163
	v_fma_f32 v24, -v38, v2, v163
	s_waitcnt vmcnt(49)
	v_lshlrev_b32_e32 v164, 16, v164
	v_fma_f32 v23, -v36, v2, v164
	s_waitcnt vmcnt(48)
	v_lshlrev_b32_e32 v165, 16, v165
	v_fma_f32 v22, -v35, v2, v165
	s_waitcnt vmcnt(47)
	v_lshlrev_b32_e32 v166, 16, v166
	v_fma_f32 v95, -v88, v2, v166
	v_mul_f32_e32 v146, v95, v95
	v_fmac_f32_e32 v146, v78, v78
	s_waitcnt vmcnt(46)
	v_lshlrev_b32_e32 v167, 16, v167
	v_fma_f32 v96, -v66, v2, v167
	v_mul_f32_e32 v145, v96, v96
	v_fmac_f32_e32 v145, v77, v77
	s_waitcnt vmcnt(45)
	v_lshlrev_b32_e32 v168, 16, v168
	v_fma_f32 v97, -v64, v2, v168
	v_mul_f32_e32 v144, v97, v97
	v_fmac_f32_e32 v144, v76, v76
	s_waitcnt vmcnt(44)
	v_lshlrev_b32_e32 v169, 16, v169
	v_fma_f32 v94, -v62, v2, v169
	v_mul_f32_e32 v143, v94, v94
	v_fmac_f32_e32 v143, v75, v75
	s_waitcnt vmcnt(43)
	v_lshlrev_b32_e32 v216, 16, v216
	v_fma_f32 v93, -v60, v2, v216
	v_mul_f32_e32 v142, v93, v93
	v_fmac_f32_e32 v142, v74, v74
	s_waitcnt vmcnt(42)
	v_lshlrev_b32_e32 v218, 16, v218
	v_fma_f32 v92, -v58, v2, v218
	v_mul_f32_e32 v141, v92, v92
	v_fmac_f32_e32 v141, v73, v73
	s_waitcnt vmcnt(41)
; __device__ __forceinline__ int crow(int r, int hi) { return (r & 3) + 8 * (r >> 2) + 4 * hi; }
; __device__ __forceinline__ int crow(int r, int hi) { return (r & 3) + 8 * (r >> 2) + 4 * hi; }
; template <int NCB, bool DIFF, bool STAT>
; __device__ __forceinline__ void attn_unit(LAS char* lds, const Params& P, int s, int head, int qb, float sref) {
;     ...
;                 for (int d0 = 0; d0 < NCB; ++d0)
; #pragma unroll
;                     for (int r = 0; r < 16; ++r) { const float o1 = bf2f(mixw[(size_t)crow(r, hi) * DM + 512 + head * 128 + d0 * 32 + r32]);
;                         const float a0 = o1 - lam * (o[d0][r] * rli[r]); o[d0][r] = a0; ss[r] += a0 * a0; }
	v_lshlrev_b32_e32 v219, 16, v219
	v_fma_f32 v91, -v56, v2, v219
	v_mul_f32_e32 v140, v91, v91
	v_fmac_f32_e32 v140, v31, v31
	s_waitcnt vmcnt(40)
	v_lshlrev_b32_e32 v220, 16, v220
	v_fma_f32 v90, -v54, v2, v220
	v_mul_f32_e32 v139, v90, v90
	v_fmac_f32_e32 v139, v30, v30
	s_waitcnt vmcnt(39)
	v_lshlrev_b32_e32 v221, 16, v221
	v_fma_f32 v89, -v51, v2, v221
	v_mul_f32_e32 v138, v89, v89
	v_fmac_f32_e32 v138, v29, v29
	s_waitcnt vmcnt(38)
	v_lshlrev_b32_e32 v222, 16, v222
	v_fma_f32 v81, -v49, v2, v222
	v_mul_f32_e32 v132, v81, v81
	v_fmac_f32_e32 v132, v28, v28
	s_waitcnt vmcnt(37)
	v_lshlrev_b32_e32 v223, 16, v223
	v_fma_f32 v80, -v47, v2, v223
	v_mul_f32_e32 v126, v80, v80
	v_fmac_f32_e32 v126, v27, v27
	s_waitcnt vmcnt(36)
	v_lshlrev_b32_e32 v224, 16, v224
	v_fma_f32 v79, -v45, v2, v224
	v_mul_f32_e32 v118, v79, v79
	v_fmac_f32_e32 v118, v26, v26
	s_waitcnt vmcnt(35)
	v_lshlrev_b32_e32 v225, 16, v225
	v_fma_f32 v98, -v43, v2, v225
	v_mul_f32_e32 v134, v98, v98
	v_fmac_f32_e32 v134, v25, v25
	s_waitcnt vmcnt(34)
	v_lshlrev_b32_e32 v226, 16, v226
	v_fma_f32 v99, -v41, v2, v226
	v_mul_f32_e32 v136, v99, v99
	v_fmac_f32_e32 v136, v24, v24
	s_waitcnt vmcnt(33)
	v_lshlrev_b32_e32 v227, 16, v227
	v_fma_f32 v100, -v39, v2, v227
	v_mul_f32_e32 v137, v100, v100
	v_fmac_f32_e32 v137, v23, v23
	s_waitcnt vmcnt(32)
	v_lshlrev_b32_e32 v228, 16, v228
	v_fma_f32 v101, -v37, v2, v228
	v_mul_f32_e32 v147, v101, v101
	v_fmac_f32_e32 v147, v22, v22
	s_waitcnt vmcnt(31)
	v_lshlrev_b32_e32 v229, 16, v229
	v_fma_f32 v116, -v70, v2, v229
	v_fmac_f32_e32 v146, v116, v116
	s_waitcnt vmcnt(30)
	v_lshlrev_b32_e32 v236, 16, v236
	v_fma_f32 v115, -v68, v2, v236
	v_fmac_f32_e32 v145, v115, v115
	s_waitcnt vmcnt(29)
	v_lshlrev_b32_e32 v237, 16, v237
	v_fma_f32 v114, -v67, v2, v237
	v_fmac_f32_e32 v144, v114, v114
	s_waitcnt vmcnt(28)
	v_lshlrev_b32_e32 v238, 16, v238
	v_fma_f32 v113, -v65, v2, v238
	v_fmac_f32_e32 v143, v113, v113
	s_waitcnt vmcnt(27)
	v_lshlrev_b32_e32 v239, 16, v239
	v_fma_f32 v112, -v63, v2, v239
	v_fmac_f32_e32 v142, v112, v112
	s_waitcnt vmcnt(26)
	v_lshlrev_b32_e32 v240, 16, v240
	v_fma_f32 v111, -v61, v2, v240
	v_fmac_f32_e32 v141, v111, v111
	s_waitcnt vmcnt(25)
	v_lshlrev_b32_e32 v241, 16, v241
	v_fma_f32 v110, -v59, v2, v241
	v_fmac_f32_e32 v140, v110, v110
	s_waitcnt vmcnt(24)
	v_lshlrev_b32_e32 v242, 16, v242
	v_fma_f32 v109, -v57, v2, v242
	v_fmac_f32_e32 v139, v109, v109
	s_waitcnt vmcnt(23)
	v_lshlrev_b32_e32 v243, 16, v243
	v_fma_f32 v108, -v55, v2, v243
	v_fmac_f32_e32 v138, v108, v108
	s_waitcnt vmcnt(22)
	v_lshlrev_b32_e32 v244, 16, v244
	v_fma_f32 v107, -v52, v2, v244
	v_fmac_f32_e32 v132, v107, v107
	s_waitcnt vmcnt(21)
	v_lshlrev_b32_e32 v245, 16, v245
	v_fma_f32 v106, -v11, v2, v245
	v_fmac_f32_e32 v126, v106, v106
	s_waitcnt vmcnt(20)
	v_lshlrev_b32_e32 v246, 16, v246
	v_fma_f32 v105, -v9, v2, v246
	v_fmac_f32_e32 v118, v105, v105
	s_waitcnt vmcnt(19)
	v_lshlrev_b32_e32 v247, 16, v247
	v_fma_f32 v104, -v7, v2, v247
	v_fmac_f32_e32 v134, v104, v104
	s_waitcnt vmcnt(18)
	v_lshlrev_b32_e32 v248, 16, v248
	v_fma_f32 v103, -v5, v2, v248
	v_fmac_f32_e32 v136, v103, v103
	s_waitcnt vmcnt(17)
	v_lshlrev_b32_e32 v249, 16, v249
	v_fma_f32 v102, -v4, v2, v249
	v_fmac_f32_e32 v137, v102, v102
	s_waitcnt vmcnt(16)
	v_lshlrev_b32_e32 v148, 16, v250
	s_waitcnt vmcnt(15)
	v_lshlrev_b32_e32 v251, 16, v251
	v_fma_f32 v117, -v72, v2, v251
	v_fmac_f32_e32 v146, v117, v117
	s_waitcnt vmcnt(14)
	v_lshlrev_b32_e32 v252, 16, v252
	v_fma_f32 v121, -v71, v2, v252
	v_fmac_f32_e32 v145, v121, v121
	s_waitcnt vmcnt(13)
	v_lshlrev_b32_e32 v253, 16, v253
	v_fma_f32 v119, -v69, v2, v253
	v_fmac_f32_e32 v144, v119, v119
	s_waitcnt vmcnt(12)
	v_lshlrev_b32_e32 v150, 16, v150
	v_fma_f32 v122, -v21, v2, v150
	v_fmac_f32_e32 v143, v122, v122
	s_waitcnt vmcnt(11)
	v_lshlrev_b32_e32 v151, 16, v151
	v_fma_f32 v120, -v20, v2, v151
	v_fmac_f32_e32 v142, v120, v120
	s_waitcnt vmcnt(10)
	v_lshlrev_b32_e32 v152, 16, v152
	v_fma_f32 v124, -v19, v2, v152
	v_fmac_f32_e32 v141, v124, v124
	s_waitcnt vmcnt(9)
	v_lshlrev_b32_e32 v153, 16, v153
	v_fma_f32 v123, -v18, v2, v153
	v_fmac_f32_e32 v140, v123, v123
	s_waitcnt vmcnt(8)
	v_lshlrev_b32_e32 v154, 16, v154
	v_fma_f32 v127, -v16, v2, v154
	v_fmac_f32_e32 v139, v127, v127
	s_waitcnt vmcnt(7)
	v_lshlrev_b32_e32 v155, 16, v155
	v_fma_f32 v125, -v15, v2, v155
	v_fmac_f32_e32 v138, v125, v125
	s_waitcnt vmcnt(6)
	v_lshlrev_b32_e32 v156, 16, v156
	v_fma_f32 v129, -v14, v2, v156
	v_fmac_f32_e32 v132, v129, v129
	s_waitcnt vmcnt(5)
	v_lshlrev_b32_e32 v157, 16, v157
	v_fma_f32 v128, -v13, v2, v157
	v_fmac_f32_e32 v126, v128, v128
	s_waitcnt vmcnt(4)
	v_lshlrev_b32_e32 v158, 16, v158
	v_fma_f32 v131, -v12, v2, v158
	v_fmac_f32_e32 v118, v131, v131
	s_waitcnt vmcnt(3)
	v_lshlrev_b32_e32 v159, 16, v159
	v_fma_f32 v130, -v10, v2, v159
	v_fmac_f32_e32 v134, v130, v130
	s_waitcnt vmcnt(2)
	v_lshlrev_b32_e32 v160, 16, v160
	v_fma_f32 v135, -v8, v2, v160
	v_fmac_f32_e32 v136, v135, v135
	s_waitcnt vmcnt(1)
	v_lshlrev_b32_e32 v161, 16, v161
	v_fma_f32 v133, -v6, v2, v161
	v_fmac_f32_e32 v137, v133, v133
	s_waitcnt vmcnt(0)
; template <int NCB, bool DIFF, bool STAT>
; __device__ __forceinline__ void attn_unit(LAS char* lds, const Params& P, int s, int head, int qb, float sref) {
;     ...
; #pragma unroll
;                 for (int r = 0; r < 16; ++r) {
; #pragma unroll
;                     for (int of = 1; of < 32; of <<= 1) ss[r] += __shfl_xor(ss[r], of);
;                     ss[r] = __builtin_amdgcn_rsqf(ss[r] * (1.0f / 128.0f) + EPS) * 0.8f;
;                 }
	v_lshlrev_b32_e32 v149, 16, v162
	v_mov_b32_e32 v32, v17
	v_pk_mul_f32 v[150:151], v[32:33], v[34:35] op_sel_hi:[1,0]
	s_nop 0
	v_pk_fma_f32 v[2:3], v[150:151], v[2:3], v[148:149] op_sel_hi:[1,0,1] neg_lo:[1,0,0] neg_hi:[1,0,0]
	s_nop 0
	v_pk_mul_f32 v[148:149], v[2:3], v[2:3]
	s_nop 0
	v_add_f32_e32 v32, v147, v148
	v_add_f32_e32 v32, v32, v149
	v_and_b32_e32 v147, 64, v235
	v_add_u32_e32 v151, 64, v147
	v_xor_b32_e32 v147, 1, v235
	v_cmp_lt_i32_e32 vcc, v147, v151
	s_nop 1
	v_cndmask_b32_e32 v147, v235, v147, vcc
	v_lshlrev_b32_e32 v147, 2, v147
	v_xor_b32_e32 v148, 2, v235
	v_cmp_lt_i32_e32 vcc, v148, v151
	s_nop 1
	v_cndmask_b32_e32 v148, v235, v148, vcc
	v_lshlrev_b32_e32 v148, 2, v148
	v_xor_b32_e32 v149, 4, v235
	v_cmp_lt_i32_e32 vcc, v149, v151
	s_nop 1
	v_cndmask_b32_e32 v149, v235, v149, vcc
	v_lshlrev_b32_e32 v149, 2, v149
	v_xor_b32_e32 v150, 8, v235
	v_cmp_lt_i32_e32 vcc, v150, v151
	s_nop 1
	v_cndmask_b32_e32 v150, v235, v150, vcc
	v_lshlrev_b32_e32 v150, 2, v150
	v_xor_b32_e32 v154, 16, v235
	v_cmp_lt_i32_e32 vcc, v154, v151
	s_nop 1
	v_cndmask_b32_e32 v151, v235, v154, vcc
	v_lshlrev_b32_e32 v151, 2, v151
	ds_bpermute_b32 v154, v147, v146
	ds_bpermute_b32 v155, v147, v145
	ds_bpermute_b32 v156, v147, v144
	ds_bpermute_b32 v157, v147, v143
	ds_bpermute_b32 v158, v147, v142
	ds_bpermute_b32 v159, v147, v141
	ds_bpermute_b32 v160, v147, v140
	ds_bpermute_b32 v161, v147, v139
	s_waitcnt lgkmcnt(7)
	v_add_f32_e32 v146, v146, v154
	ds_bpermute_b32 v162, v147, v138
	s_waitcnt lgkmcnt(7)
	v_add_f32_e32 v145, v145, v155
	ds_bpermute_b32 v163, v147, v132
	s_waitcnt lgkmcnt(7)
	v_add_f32_e32 v144, v144, v156
	ds_bpermute_b32 v164, v147, v126
	s_waitcnt lgkmcnt(7)
	v_add_f32_e32 v143, v143, v157
	ds_bpermute_b32 v165, v147, v118
	s_waitcnt lgkmcnt(7)
	v_add_f32_e32 v142, v142, v158
	ds_bpermute_b32 v166, v147, v134
	s_waitcnt lgkmcnt(7)
	v_add_f32_e32 v141, v141, v159
	ds_bpermute_b32 v167, v147, v136
	s_waitcnt lgkmcnt(7)
	v_add_f32_e32 v140, v140, v160
	ds_bpermute_b32 v168, v147, v137
	s_waitcnt lgkmcnt(7)
	v_add_f32_e32 v139, v139, v161
	ds_bpermute_b32 v169, v147, v32
	s_waitcnt lgkmcnt(7)
	v_add_f32_e32 v138, v138, v162
	s_waitcnt lgkmcnt(6)
	v_add_f32_e32 v132, v132, v163
	s_waitcnt lgkmcnt(5)
	v_add_f32_e32 v126, v126, v164
	s_waitcnt lgkmcnt(4)
	v_add_f32_e32 v118, v118, v165
	s_waitcnt lgkmcnt(3)
	v_add_f32_e32 v134, v134, v166
	s_waitcnt lgkmcnt(2)
	v_add_f32_e32 v136, v136, v167
	s_waitcnt lgkmcnt(1)
	v_add_f32_e32 v137, v137, v168
	s_waitcnt lgkmcnt(0)
	v_add_f32_e32 v32, v32, v169
	ds_bpermute_b32 v154, v148, v146
	ds_bpermute_b32 v155, v148, v145
	ds_bpermute_b32 v156, v148, v144
	ds_bpermute_b32 v157, v148, v143
	ds_bpermute_b32 v158, v148, v142
	ds_bpermute_b32 v159, v148, v141
	ds_bpermute_b32 v160, v148, v140
	ds_bpermute_b32 v161, v148, v139
	s_waitcnt lgkmcnt(7)
	v_add_f32_e32 v146, v146, v154
	ds_bpermute_b32 v162, v148, v138
	s_waitcnt lgkmcnt(7)
	v_add_f32_e32 v145, v145, v155
	ds_bpermute_b32 v163, v148, v132
	s_waitcnt lgkmcnt(7)
	v_add_f32_e32 v144, v144, v156
	ds_bpermute_b32 v164, v148, v126
	s_waitcnt lgkmcnt(7)
	v_add_f32_e32 v143, v143, v157
	ds_bpermute_b32 v165, v148, v118
	s_waitcnt lgkmcnt(7)
	v_add_f32_e32 v142, v142, v158
	ds_bpermute_b32 v166, v148, v134
	s_waitcnt lgkmcnt(7)
	v_add_f32_e32 v141, v141, v159
	ds_bpermute_b32 v167, v148, v136
	s_waitcnt lgkmcnt(7)
	v_add_f32_e32 v140, v140, v160
	ds_bpermute_b32 v168, v148, v137
	s_waitcnt lgkmcnt(7)
	v_add_f32_e32 v139, v139, v161
	ds_bpermute_b32 v169, v148, v32
	s_waitcnt lgkmcnt(7)
	v_add_f32_e32 v138, v138, v162
	s_waitcnt lgkmcnt(6)
	v_add_f32_e32 v132, v132, v163
	s_waitcnt lgkmcnt(5)
	v_add_f32_e32 v126, v126, v164
	s_waitcnt lgkmcnt(4)
	v_add_f32_e32 v118, v118, v165
	s_waitcnt lgkmcnt(3)
	v_add_f32_e32 v134, v134, v166
	s_waitcnt lgkmcnt(2)
	v_add_f32_e32 v136, v136, v167
	s_waitcnt lgkmcnt(1)
	v_add_f32_e32 v137, v137, v168
	s_waitcnt lgkmcnt(0)
	v_add_f32_e32 v32, v32, v169
	ds_bpermute_b32 v154, v149, v146
	ds_bpermute_b32 v155, v149, v145
	ds_bpermute_b32 v156, v149, v144
	ds_bpermute_b32 v157, v149, v143
	ds_bpermute_b32 v158, v149, v142
	ds_bpermute_b32 v159, v149, v141
	ds_bpermute_b32 v160, v149, v140
	ds_bpermute_b32 v161, v149, v139
	s_waitcnt lgkmcnt(7)
	v_add_f32_e32 v146, v146, v154
	ds_bpermute_b32 v162, v149, v138
	s_waitcnt lgkmcnt(7)
	v_add_f32_e32 v145, v145, v155
	ds_bpermute_b32 v163, v149, v132
	s_waitcnt lgkmcnt(7)
	v_add_f32_e32 v144, v144, v156
	ds_bpermute_b32 v164, v149, v126
	s_waitcnt lgkmcnt(7)
	v_add_f32_e32 v143, v143, v157
	ds_bpermute_b32 v165, v149, v118
	s_waitcnt lgkmcnt(7)
	v_add_f32_e32 v142, v142, v158
	ds_bpermute_b32 v166, v149, v134
	s_waitcnt lgkmcnt(7)
	v_add_f32_e32 v141, v141, v159
	ds_bpermute_b32 v167, v149, v136
	s_waitcnt lgkmcnt(7)
	v_add_f32_e32 v140, v140, v160
	ds_bpermute_b32 v168, v149, v137
	s_waitcnt lgkmcnt(7)
	v_add_f32_e32 v139, v139, v161
	ds_bpermute_b32 v169, v149, v32
	s_waitcnt lgkmcnt(7)
	v_add_f32_e32 v138, v138, v162
	s_waitcnt lgkmcnt(6)
	v_add_f32_e32 v132, v132, v163
	s_waitcnt lgkmcnt(5)
	v_add_f32_e32 v126, v126, v164
	s_waitcnt lgkmcnt(4)
	v_add_f32_e32 v118, v118, v165
	s_waitcnt lgkmcnt(3)
	v_add_f32_e32 v134, v134, v166
	s_waitcnt lgkmcnt(2)
	v_add_f32_e32 v136, v136, v167
	s_waitcnt lgkmcnt(1)
	v_add_f32_e32 v137, v137, v168
	s_waitcnt lgkmcnt(0)
	v_add_f32_e32 v32, v32, v169
	ds_bpermute_b32 v154, v150, v146
	ds_bpermute_b32 v155, v150, v145
	ds_bpermute_b32 v156, v150, v144
	ds_bpermute_b32 v157, v150, v143
	ds_bpermute_b32 v158, v150, v142
	ds_bpermute_b32 v159, v150, v141
	ds_bpermute_b32 v160, v150, v140
	ds_bpermute_b32 v161, v150, v139
	s_waitcnt lgkmcnt(7)
; __device__ __forceinline__ unsigned f2bf(float f) { unsigned u = __builtin_bit_cast(unsigned, f); return (u + 0x7fffu + ((u >> 16) & 1u)) >> 16; }
; __device__ __forceinline__ int crow(int r, int hi) { return (r & 3) + 8 * (r >> 2) + 4 * hi; }
; __device__ __forceinline__ int crow(int r, int hi) { return (r & 3) + 8 * (r >> 2) + 4 * hi; }
; template <int NCB, bool DIFF, bool STAT>
; __device__ __forceinline__ void attn_unit(LAS char* lds, const Params& P, int s, int head, int qb, float sref) {
;     ...
; #pragma unroll
;                 for (int r = 0; r < 16; ++r) {
; #pragma unroll
;                     for (int of = 1; of < 32; of <<= 1) ss[r] += __shfl_xor(ss[r], of);
;                     ss[r] = __builtin_amdgcn_rsqf(ss[r] * (1.0f / 128.0f) + EPS) * 0.8f;
;                 }
;                 float gs[NCB];
; #pragma unroll
;                 for (int d0 = 0; d0 < NCB; ++d0) gs[d0] = P.in[15][d0 * 32 + r32];
; #pragma unroll
;                 for (int r = 0; r < 16; ++r) { const int orow = crow(r, hi);
; #pragma unroll
;                     for (int d0 = 0; d0 < NCB; ++d0) mixw[(size_t)orow * DM + 512 + head * 128 + d0 * 32 + r32] = (bf16)f2bf(o[d0][r] * ss[r] * gs[d0]); }
	v_add_f32_e32 v146, v146, v154
	ds_bpermute_b32 v162, v150, v138
	s_waitcnt lgkmcnt(7)
	v_add_f32_e32 v145, v145, v155
	ds_bpermute_b32 v163, v150, v132
	s_waitcnt lgkmcnt(7)
	v_add_f32_e32 v144, v144, v156
	ds_bpermute_b32 v164, v150, v126
	s_waitcnt lgkmcnt(7)
	v_add_f32_e32 v143, v143, v157
	ds_bpermute_b32 v165, v150, v118
	s_waitcnt lgkmcnt(7)
	v_add_f32_e32 v142, v142, v158
	ds_bpermute_b32 v166, v150, v134
	s_waitcnt lgkmcnt(7)
	v_add_f32_e32 v141, v141, v159
	ds_bpermute_b32 v167, v150, v136
	s_waitcnt lgkmcnt(7)
	v_add_f32_e32 v140, v140, v160
	ds_bpermute_b32 v168, v150, v137
	s_waitcnt lgkmcnt(7)
	v_add_f32_e32 v139, v139, v161
	ds_bpermute_b32 v169, v150, v32
	s_waitcnt lgkmcnt(7)
	v_add_f32_e32 v138, v138, v162
	s_waitcnt lgkmcnt(6)
	v_add_f32_e32 v132, v132, v163
	s_waitcnt lgkmcnt(5)
	v_add_f32_e32 v126, v126, v164
	s_waitcnt lgkmcnt(4)
	v_add_f32_e32 v118, v118, v165
	s_waitcnt lgkmcnt(3)
	v_add_f32_e32 v134, v134, v166
	s_waitcnt lgkmcnt(2)
	v_add_f32_e32 v136, v136, v167
	s_waitcnt lgkmcnt(1)
	v_add_f32_e32 v137, v137, v168
	s_waitcnt lgkmcnt(0)
	v_add_f32_e32 v32, v32, v169
	ds_bpermute_b32 v154, v151, v146
	ds_bpermute_b32 v155, v151, v145
	ds_bpermute_b32 v156, v151, v144
	ds_bpermute_b32 v157, v151, v143
	ds_bpermute_b32 v158, v151, v142
	ds_bpermute_b32 v159, v151, v141
	ds_bpermute_b32 v160, v151, v140
	ds_bpermute_b32 v161, v151, v139
	s_waitcnt lgkmcnt(7)
	v_add_f32_e32 v146, v146, v154
	ds_bpermute_b32 v162, v151, v138
	s_waitcnt lgkmcnt(7)
	v_add_f32_e32 v145, v145, v155
	ds_bpermute_b32 v163, v151, v132
	s_waitcnt lgkmcnt(7)
	v_add_f32_e32 v144, v144, v156
	ds_bpermute_b32 v164, v151, v126
	s_waitcnt lgkmcnt(7)
	v_add_f32_e32 v143, v143, v157
	ds_bpermute_b32 v165, v151, v118
	s_waitcnt lgkmcnt(7)
	v_add_f32_e32 v142, v142, v158
	ds_bpermute_b32 v166, v151, v134
	s_waitcnt lgkmcnt(7)
	v_add_f32_e32 v141, v141, v159
	ds_bpermute_b32 v167, v151, v136
	s_waitcnt lgkmcnt(7)
	v_add_f32_e32 v140, v140, v160
	ds_bpermute_b32 v168, v151, v137
	s_waitcnt lgkmcnt(7)
	v_add_f32_e32 v139, v139, v161
	ds_bpermute_b32 v169, v151, v32
	s_waitcnt lgkmcnt(7)
	v_add_f32_e32 v138, v138, v162
	s_waitcnt lgkmcnt(6)
	v_add_f32_e32 v132, v132, v163
	s_waitcnt lgkmcnt(5)
	v_add_f32_e32 v126, v126, v164
	s_waitcnt lgkmcnt(4)
	v_add_f32_e32 v118, v118, v165
	s_waitcnt lgkmcnt(3)
	v_add_f32_e32 v134, v134, v166
	s_waitcnt lgkmcnt(2)
	v_add_f32_e32 v136, v136, v167
	s_waitcnt lgkmcnt(1)
	v_add_f32_e32 v137, v137, v168
	s_waitcnt lgkmcnt(0)
	v_add_f32_e32 v32, v32, v169
	v_fmamk_f32 v146, v146, 0x3c000000, v234
	v_fmamk_f32 v145, v145, 0x3c000000, v234
	v_fmamk_f32 v144, v144, 0x3c000000, v234
	v_fmamk_f32 v143, v143, 0x3c000000, v234
	v_fmamk_f32 v142, v142, 0x3c000000, v234
	v_fmamk_f32 v141, v141, 0x3c000000, v234
	v_fmamk_f32 v140, v140, 0x3c000000, v234
	v_fmamk_f32 v139, v139, 0x3c000000, v234
	v_fmamk_f32 v138, v138, 0x3c000000, v234
	v_fmamk_f32 v132, v132, 0x3c000000, v234
	v_fmamk_f32 v126, v126, 0x3c000000, v234
	v_fmamk_f32 v118, v118, 0x3c000000, v234
	v_fmamk_f32 v134, v134, 0x3c000000, v234
	v_fmamk_f32 v136, v136, 0x3c000000, v234
	v_fmamk_f32 v137, v137, 0x3c000000, v234
	v_rsq_f32_e32 v146, v146
	v_rsq_f32_e32 v145, v145
	v_rsq_f32_e32 v144, v144
	v_rsq_f32_e32 v143, v143
	v_rsq_f32_e32 v142, v142
	v_rsq_f32_e32 v141, v141
	v_rsq_f32_e32 v140, v140
	v_rsq_f32_e32 v139, v139
	v_rsq_f32_e32 v138, v138
	v_rsq_f32_e32 v132, v132
	v_rsq_f32_e32 v126, v126
	v_rsq_f32_e32 v118, v118
	v_rsq_f32_e32 v134, v134
	v_rsq_f32_e32 v136, v136
	v_rsq_f32_e32 v137, v137
	v_mul_f32_e32 v146, 0x3f4ccccd, v146
	v_mul_f32_e32 v145, 0x3f4ccccd, v145
	v_mul_f32_e32 v144, 0x3f4ccccd, v144
	v_mul_f32_e32 v143, 0x3f4ccccd, v143
	v_mul_f32_e32 v142, 0x3f4ccccd, v142
	v_mul_f32_e32 v141, 0x3f4ccccd, v141
	v_mul_f32_e32 v140, 0x3f4ccccd, v140
	v_mul_f32_e32 v139, 0x3f4ccccd, v139
	v_mul_f32_e32 v138, 0x3f4ccccd, v138
	v_mul_f32_e32 v132, 0x3f4ccccd, v132
	v_mul_f32_e32 v126, 0x3f4ccccd, v126
	v_mul_f32_e32 v153, 0x3f4ccccd, v118
	v_mul_f32_e32 v152, 0x3f4ccccd, v134
	v_mul_f32_e32 v134, 0x3f4ccccd, v136
	v_mul_f32_e32 v118, 0x3f4ccccd, v137
	v_mul_f32_e32 v78, v78, v146
	v_mul_f32_e32 v77, v77, v145
	v_mul_f32_e32 v76, v76, v144
	v_mul_f32_e32 v75, v75, v143
	v_mul_f32_e32 v74, v74, v142
	v_mul_f32_e32 v73, v73, v141
	v_mul_f32_e32 v31, v31, v140
	v_mul_f32_e32 v30, v30, v139
	v_mul_f32_e32 v29, v29, v138
	v_mul_f32_e32 v28, v28, v132
	v_mul_f32_e32 v27, v27, v126
	v_mul_f32_e32 v26, v26, v153
	v_mul_f32_e32 v25, v25, v152
	v_mul_f32_e32 v24, v24, v134
	v_mul_f32_e32 v23, v23, v118
	global_load_dword v136, v[202:203], off
	global_load_dword v137, v[202:203], off offset:128
	global_load_dword v147, v[202:203], off offset:256
	global_load_dword v148, v[202:203], off offset:384
	v_fmamk_f32 v32, v32, 0x3c000000, v234
	v_rsq_f32_e32 v32, v32
	s_waitcnt vmcnt(3)
	v_mul_f32_e32 v78, v78, v136
	v_bfe_u32 v149, v78, 16, 1
	v_add3_u32 v78, v78, v149, s70
	global_store_short_d16_hi v[172:173], v78, off offset:1024
	v_mul_f32_e32 v78, v95, v146
	s_waitcnt vmcnt(3)
	v_mul_f32_e32 v78, v78, v137
	v_bfe_u32 v95, v78, 16, 1
	v_add3_u32 v78, v78, v95, s70
	global_store_short_d16_hi v[172:173], v78, off offset:1088
	v_mul_f32_e32 v78, v116, v146
	s_waitcnt vmcnt(3)
	v_mul_f32_e32 v78, v78, v147
	v_bfe_u32 v95, v78, 16, 1
	v_add3_u32 v78, v78, v95, s70
	global_store_short_d16_hi v[172:173], v78, off offset:1152
	v_mul_f32_e32 v78, v117, v146
	s_waitcnt vmcnt(3)
; __device__ __forceinline__ unsigned f2bf(float f) { unsigned u = __builtin_bit_cast(unsigned, f); return (u + 0x7fffu + ((u >> 16) & 1u)) >> 16; }
; __device__ __forceinline__ int crow(int r, int hi) { return (r & 3) + 8 * (r >> 2) + 4 * hi; }
; __device__ __forceinline__ int crow(int r, int hi) { return (r & 3) + 8 * (r >> 2) + 4 * hi; }
; template <int NCB, bool DIFF, bool STAT>
; __device__ __forceinline__ void attn_unit(LAS char* lds, const Params& P, int s, int head, int qb, float sref) {
;     ...
; #pragma unroll
;                 for (int r = 0; r < 16; ++r) { const int orow = crow(r, hi);
; #pragma unroll
;                     for (int d0 = 0; d0 < NCB; ++d0) mixw[(size_t)orow * DM + 512 + head * 128 + d0 * 32 + r32] = (bf16)f2bf(o[d0][r] * ss[r] * gs[d0]); }
	v_mul_f32_e32 v78, v78, v148
	v_bfe_u32 v95, v78, 16, 1
	v_add3_u32 v78, v78, v95, s70
	v_mul_f32_e32 v77, v77, v136
	global_store_short_d16_hi v[172:173], v78, off offset:1216
	v_bfe_u32 v78, v77, 16, 1
	v_add3_u32 v77, v77, v78, s70
	global_store_short_d16_hi v[172:173], v77, off offset:3072
	v_mul_f32_e32 v77, v96, v145
	v_mul_f32_e32 v77, v77, v137
	v_bfe_u32 v78, v77, 16, 1
	v_add3_u32 v77, v77, v78, s70
	global_store_short_d16_hi v[172:173], v77, off offset:3136
	v_mul_f32_e32 v77, v115, v145
	v_mul_f32_e32 v77, v77, v147
	v_bfe_u32 v78, v77, 16, 1
	v_add3_u32 v77, v77, v78, s70
	global_store_short_d16_hi v[172:173], v77, off offset:3200
	v_mul_f32_e32 v77, v121, v145
	v_mul_f32_e32 v77, v77, v148
	v_bfe_u32 v78, v77, 16, 1
	v_add3_u32 v77, v77, v78, s70
	v_mul_f32_e32 v76, v76, v136
	global_store_short_d16_hi v[172:173], v77, off offset:3264
	v_bfe_u32 v77, v76, 16, 1
	v_add3_u32 v76, v76, v77, s70
	global_store_short_d16_hi v[174:175], v76, off
	v_mul_f32_e32 v76, v97, v144
	v_mul_f32_e32 v76, v76, v137
	v_bfe_u32 v77, v76, 16, 1
	v_add3_u32 v76, v76, v77, s70
	global_store_short_d16_hi v[174:175], v76, off offset:64
	v_mul_f32_e32 v76, v114, v144
	v_mul_f32_e32 v76, v76, v147
	v_bfe_u32 v77, v76, 16, 1
	v_add3_u32 v76, v76, v77, s70
	global_store_short_d16_hi v[174:175], v76, off offset:128
	v_mul_f32_e32 v76, v119, v144
	v_mul_f32_e32 v76, v76, v148
	v_bfe_u32 v77, v76, 16, 1
	v_add3_u32 v76, v76, v77, s70
	v_mul_f32_e32 v75, v75, v136
	global_store_short_d16_hi v[174:175], v76, off offset:192
	v_bfe_u32 v76, v75, 16, 1
	v_add3_u32 v75, v75, v76, s70
	global_store_short_d16_hi v[176:177], v75, off
	v_mul_f32_e32 v75, v94, v143
	v_mul_f32_e32 v75, v75, v137
	v_bfe_u32 v76, v75, 16, 1
	v_add3_u32 v75, v75, v76, s70
	global_store_short_d16_hi v[176:177], v75, off offset:64
	v_mul_f32_e32 v75, v113, v143
	v_mul_f32_e32 v75, v75, v147
	v_bfe_u32 v76, v75, 16, 1
	v_add3_u32 v75, v75, v76, s70
	global_store_short_d16_hi v[176:177], v75, off offset:128
	v_mul_f32_e32 v75, v122, v143
	v_mul_f32_e32 v75, v75, v148
	v_bfe_u32 v76, v75, 16, 1
	v_add3_u32 v75, v75, v76, s70
	v_mul_f32_e32 v74, v74, v136
	global_store_short_d16_hi v[176:177], v75, off offset:192
	v_bfe_u32 v75, v74, 16, 1
	v_add3_u32 v74, v74, v75, s70
	global_store_short_d16_hi v[178:179], v74, off
	v_mul_f32_e32 v74, v93, v142
	v_mul_f32_e32 v74, v74, v137
	v_bfe_u32 v75, v74, 16, 1
	v_add3_u32 v74, v74, v75, s70
	global_store_short_d16_hi v[178:179], v74, off offset:64
	v_mul_f32_e32 v74, v112, v142
	v_mul_f32_e32 v74, v74, v147
	v_bfe_u32 v75, v74, 16, 1
	v_add3_u32 v74, v74, v75, s70
	global_store_short_d16_hi v[178:179], v74, off offset:128
	v_mul_f32_e32 v74, v120, v142
	v_mul_f32_e32 v74, v74, v148
	v_bfe_u32 v75, v74, 16, 1
	v_add3_u32 v74, v74, v75, s70
	v_mul_f32_e32 v73, v73, v136
	global_store_short_d16_hi v[178:179], v74, off offset:192
	v_bfe_u32 v74, v73, 16, 1
	v_add3_u32 v73, v73, v74, s70
	global_store_short_d16_hi v[180:181], v73, off
	v_mul_f32_e32 v73, v92, v141
	v_mul_f32_e32 v73, v73, v137
	v_bfe_u32 v74, v73, 16, 1
	v_add3_u32 v73, v73, v74, s70
	global_store_short_d16_hi v[180:181], v73, off offset:64
	v_mul_f32_e32 v73, v111, v141
	v_mul_f32_e32 v73, v73, v147
	v_bfe_u32 v74, v73, 16, 1
	v_add3_u32 v73, v73, v74, s70
	global_store_short_d16_hi v[180:181], v73, off offset:128
	v_mul_f32_e32 v73, v124, v141
	v_mul_f32_e32 v73, v73, v148
	v_bfe_u32 v74, v73, 16, 1
	v_add3_u32 v73, v73, v74, s70
	v_mul_f32_e32 v31, v31, v136
	global_store_short_d16_hi v[180:181], v73, off offset:192
	v_bfe_u32 v73, v31, 16, 1
	v_add3_u32 v31, v31, v73, s70
	global_store_short_d16_hi v[182:183], v31, off
	v_mul_f32_e32 v31, v91, v140
	v_mul_f32_e32 v31, v31, v137
	v_bfe_u32 v73, v31, 16, 1
	v_add3_u32 v31, v31, v73, s70
	global_store_short_d16_hi v[182:183], v31, off offset:64
	v_mul_f32_e32 v31, v110, v140
	v_mul_f32_e32 v31, v31, v147
	v_bfe_u32 v73, v31, 16, 1
	v_add3_u32 v31, v31, v73, s70
	global_store_short_d16_hi v[182:183], v31, off offset:128
	v_mul_f32_e32 v31, v123, v140
	v_mul_f32_e32 v31, v31, v148
	v_bfe_u32 v73, v31, 16, 1
	v_add3_u32 v31, v31, v73, s70
	v_mul_f32_e32 v30, v30, v136
	global_store_short_d16_hi v[182:183], v31, off offset:192
	v_bfe_u32 v31, v30, 16, 1
	v_add3_u32 v30, v30, v31, s70
	global_store_short_d16_hi v[184:185], v30, off
	v_mul_f32_e32 v30, v90, v139
	v_mul_f32_e32 v30, v30, v137
	v_bfe_u32 v31, v30, 16, 1
	v_add3_u32 v30, v30, v31, s70
	global_store_short_d16_hi v[184:185], v30, off offset:64
	v_mul_f32_e32 v30, v109, v139
	v_mul_f32_e32 v30, v30, v147
	v_bfe_u32 v31, v30, 16, 1
	v_add3_u32 v30, v30, v31, s70
	global_store_short_d16_hi v[184:185], v30, off offset:128
	v_mul_f32_e32 v30, v127, v139
	v_mul_f32_e32 v30, v30, v148
	v_bfe_u32 v31, v30, 16, 1
	v_add3_u32 v30, v30, v31, s70
	v_mul_f32_e32 v29, v29, v136
	global_store_short_d16_hi v[184:185], v30, off offset:192
	v_bfe_u32 v30, v29, 16, 1
	v_add3_u32 v29, v29, v30, s70
	global_store_short_d16_hi v[186:187], v29, off
	v_mul_f32_e32 v29, v89, v138
	v_mul_f32_e32 v29, v29, v137
	v_bfe_u32 v30, v29, 16, 1
; __device__ __forceinline__ unsigned f2bf(float f) { unsigned u = __builtin_bit_cast(unsigned, f); return (u + 0x7fffu + ((u >> 16) & 1u)) >> 16; }
; __device__ __forceinline__ int crow(int r, int hi) { return (r & 3) + 8 * (r >> 2) + 4 * hi; }
; __device__ __forceinline__ int crow(int r, int hi) { return (r & 3) + 8 * (r >> 2) + 4 * hi; }
; template <int NCB, bool DIFF, bool STAT>
; __device__ __forceinline__ void attn_unit(LAS char* lds, const Params& P, int s, int head, int qb, float sref) {
;     ...
; #pragma unroll
;                 for (int r = 0; r < 16; ++r) { const int orow = crow(r, hi);
; #pragma unroll
;                     for (int d0 = 0; d0 < NCB; ++d0) mixw[(size_t)orow * DM + 512 + head * 128 + d0 * 32 + r32] = (bf16)f2bf(o[d0][r] * ss[r] * gs[d0]); }
	v_add3_u32 v29, v29, v30, s70
	global_store_short_d16_hi v[186:187], v29, off offset:64
	v_mul_f32_e32 v29, v108, v138
	v_mul_f32_e32 v29, v29, v147
	v_bfe_u32 v30, v29, 16, 1
	v_add3_u32 v29, v29, v30, s70
	global_store_short_d16_hi v[186:187], v29, off offset:128
	v_mul_f32_e32 v29, v125, v138
	v_mul_f32_e32 v29, v29, v148
	v_bfe_u32 v30, v29, 16, 1
	v_add3_u32 v29, v29, v30, s70
	v_mul_f32_e32 v28, v28, v136
	global_store_short_d16_hi v[186:187], v29, off offset:192
	v_bfe_u32 v29, v28, 16, 1
	v_add3_u32 v28, v28, v29, s70
	global_store_short_d16_hi v[188:189], v28, off
	v_mul_f32_e32 v28, v81, v132
	v_mul_f32_e32 v28, v28, v137
	v_bfe_u32 v29, v28, 16, 1
	v_add3_u32 v28, v28, v29, s70
	global_store_short_d16_hi v[188:189], v28, off offset:64
	v_mul_f32_e32 v28, v107, v132
	v_mul_f32_e32 v28, v28, v147
	v_bfe_u32 v29, v28, 16, 1
	v_add3_u32 v28, v28, v29, s70
	global_store_short_d16_hi v[188:189], v28, off offset:128
	v_mul_f32_e32 v28, v129, v132
	v_mul_f32_e32 v28, v28, v148
	v_bfe_u32 v29, v28, 16, 1
	v_add3_u32 v28, v28, v29, s70
	v_mul_f32_e32 v27, v27, v136
	global_store_short_d16_hi v[188:189], v28, off offset:192
	v_bfe_u32 v28, v27, 16, 1
	v_add3_u32 v27, v27, v28, s70
	global_store_short_d16_hi v[190:191], v27, off
	v_mul_f32_e32 v27, v80, v126
	v_mul_f32_e32 v27, v27, v137
	v_bfe_u32 v28, v27, 16, 1
	v_add3_u32 v27, v27, v28, s70
	global_store_short_d16_hi v[190:191], v27, off offset:64
	v_mul_f32_e32 v27, v106, v126
	v_mul_f32_e32 v27, v27, v147
	v_bfe_u32 v28, v27, 16, 1
	v_add3_u32 v27, v27, v28, s70
	global_store_short_d16_hi v[190:191], v27, off offset:128
	v_mul_f32_e32 v27, v128, v126
	v_mul_f32_e32 v27, v27, v148
	v_bfe_u32 v28, v27, 16, 1
	v_add3_u32 v27, v27, v28, s70
	v_mul_f32_e32 v26, v26, v136
	global_store_short_d16_hi v[190:191], v27, off offset:192
	v_bfe_u32 v27, v26, 16, 1
	v_add3_u32 v26, v26, v27, s70
	global_store_short_d16_hi v[192:193], v26, off
	v_mul_f32_e32 v26, v79, v153
	v_mul_f32_e32 v26, v26, v137
	v_bfe_u32 v27, v26, 16, 1
	v_add3_u32 v26, v26, v27, s70
	global_store_short_d16_hi v[192:193], v26, off offset:64
	v_mul_f32_e32 v26, v105, v153
	v_mul_f32_e32 v26, v26, v147
	v_bfe_u32 v27, v26, 16, 1
	v_add3_u32 v26, v26, v27, s70
	global_store_short_d16_hi v[192:193], v26, off offset:128
	v_mul_f32_e32 v26, v131, v153
	v_mul_f32_e32 v26, v26, v148
	v_bfe_u32 v27, v26, 16, 1
	v_add3_u32 v26, v26, v27, s70
	v_mul_f32_e32 v25, v25, v136
	global_store_short_d16_hi v[192:193], v26, off offset:192
	v_bfe_u32 v26, v25, 16, 1
	v_add3_u32 v25, v25, v26, s70
	global_store_short_d16_hi v[194:195], v25, off
	v_mul_f32_e32 v25, v98, v152
	v_mul_f32_e32 v25, v25, v137
	v_bfe_u32 v26, v25, 16, 1
	v_add3_u32 v25, v25, v26, s70
	global_store_short_d16_hi v[194:195], v25, off offset:64
	v_mul_f32_e32 v25, v104, v152
	v_mul_f32_e32 v25, v25, v147
	v_bfe_u32 v26, v25, 16, 1
	v_add3_u32 v25, v25, v26, s70
	global_store_short_d16_hi v[194:195], v25, off offset:128
	v_mul_f32_e32 v25, v130, v152
	v_mul_f32_e32 v25, v25, v148
	v_bfe_u32 v26, v25, 16, 1
	v_add3_u32 v25, v25, v26, s70
	v_mul_f32_e32 v24, v24, v136
	global_store_short_d16_hi v[194:195], v25, off offset:192
	v_bfe_u32 v25, v24, 16, 1
	v_add3_u32 v24, v24, v25, s70
	global_store_short_d16_hi v[196:197], v24, off
	v_mul_f32_e32 v24, v99, v134
	v_mul_f32_e32 v24, v24, v137
	v_bfe_u32 v25, v24, 16, 1
	v_add3_u32 v24, v24, v25, s70
	global_store_short_d16_hi v[196:197], v24, off offset:64
	v_mul_f32_e32 v24, v103, v134
	v_mul_f32_e32 v24, v24, v147
	v_bfe_u32 v25, v24, 16, 1
	v_add3_u32 v24, v24, v25, s70
	global_store_short_d16_hi v[196:197], v24, off offset:128
	v_mul_f32_e32 v24, v135, v134
	v_mul_f32_e32 v24, v24, v148
	v_bfe_u32 v25, v24, 16, 1
	v_add3_u32 v24, v24, v25, s70
	v_mul_f32_e32 v23, v136, v23
	global_store_short_d16_hi v[196:197], v24, off offset:192
	v_bfe_u32 v24, v23, 16, 1
	v_add3_u32 v23, v23, v24, s70
	global_store_short_d16_hi v[198:199], v23, off
	v_mul_f32_e32 v23, v100, v118
	v_mul_f32_e32 v23, v23, v137
	v_bfe_u32 v24, v23, 16, 1
	v_add3_u32 v23, v23, v24, s70
	global_store_short_d16_hi v[198:199], v23, off offset:64
	v_mul_f32_e32 v23, v102, v118
	v_mul_f32_e32 v23, v23, v147
	v_bfe_u32 v24, v23, 16, 1
	v_add3_u32 v23, v23, v24, s70
	global_store_short_d16_hi v[198:199], v23, off offset:128
	v_mul_f32_e32 v23, v133, v118
	v_mul_f32_e32 v32, 0x3f4ccccd, v32
	v_mul_f32_e32 v23, v23, v148
	v_bfe_u32 v24, v23, 16, 1
	v_mul_f32_e32 v22, v22, v32
	v_add3_u32 v23, v23, v24, s70
	v_mul_f32_e32 v22, v136, v22
	global_store_short_d16_hi v[198:199], v23, off offset:192
	v_bfe_u32 v23, v22, 16, 1
	v_add3_u32 v22, v22, v23, s70
	global_store_short_d16_hi v[200:201], v22, off
	v_mul_f32_e32 v22, v101, v32
	v_mul_f32_e32 v22, v137, v22
	v_bfe_u32 v23, v22, 16, 1
	v_mul_f32_e32 v2, v2, v32
	v_add3_u32 v22, v22, v23, s70
	v_mul_f32_e32 v2, v147, v2
	global_store_short_d16_hi v[200:201], v22, off offset:64
	v_bfe_u32 v22, v2, 16, 1
	v_add3_u32 v2, v2, v22, s70
	global_store_short_d16_hi v[200:201], v2, off offset:128
	v_mul_f32_e32 v2, v3, v32
	v_mul_f32_e32 v2, v148, v2

; #define LAS __attribute__((address_space(3)))
; #define WAIT_BAR() asm volatile("s_waitcnt vmcnt(0) lgkmcnt(0)\n\ts_barrier" ::: "memory")
; template <int NCB, bool DIFF, bool STAT>
; __device__ __forceinline__ void attn_unit(LAS char* lds, const Params& P, int s, int head, int qb, float sref) {
;     ...
;         __syncthreads();
;         DMA(0, 0); DMA(1, 1); DMA(2, 2);
;         bf16x8 qr[4];
; #pragma unroll
;         for (int d0 = 0; d0 < 4; ++d0) qr[d0] = *(const bf16x8*)(Qw + (size_t)r32 * 64 + d0 * 16 + hi * 8);
;         constexpr bool ZREF = STAT && !DIFF;
;         float m_reg = (STAT && !ZREF) ? sref : 0.f, l_reg = 0.f, cb = 0.f; bool moved = true;
;         if constexpr (STAT && DIFF) {
;             float q2 = 0.f;
; #pragma unroll
;             for (int d0 = 0; d0 < 4; ++d0)
; #pragma unroll
;                 for (int i = 0; i < 8; ++i) { const float f = __builtin_bit_cast(float, (unsigned)(unsigned short)qr[d0][i] << 16); q2 += f * f; }
;             { auto rr = __builtin_amdgcn_permlane32_swap(__float_as_uint(q2), __float_as_uint(q2), false, false); q2 = __uint_as_float(rr[0]) + __uint_as_float(rr[1]); }
;             const float kn2 = __uint_as_float(((const unsigned*)(ws + WS_BAR))[3800 + s * 8 + head * 2 + mp]);
;             m_reg = __builtin_sqrtf(q2 * kn2) * 1.001f + 0.01f + sref;
;         }
;         f32x16 negm;
; #pragma unroll
;         for (int d = 0; d < NCB; ++d) o[d] = f32x16{};
;         f32x16 pA0, pA1, pB0, pB1; float alA = 1.f, alB = 1.f;
;         u32x4 pw[4];
;         int bm = 0, ix = 0;
;         WAIT_BAR();
;         BMODE(0); NEGM();
;         { const LAS char* kp_ = kp0;
; #pragma unroll
;           for (int d0 = 0; d0 < 4; ++d0) { const bf16x8 b0 = *(const LAS bf16x8*)(kp_ + d0 * 2048), b1 = *(const LAS bf16x8*)(kp_ + d0 * 2048 + 512);
;               if (d0 == 0) { if constexpr (ZREF) { pA0 = MFMA32(b0, qr[0], f32x16{}); pA1 = MFMA32(b1, qr[0], f32x16{}); } else { pA0 = MFMA32(b0, qr[0], negm); pA1 = MFMA32(b1, qr[0], negm); } } else { pA0 = MFMA32(b0, qr[d0], pA0); pA1 = MFMA32(b1, qr[d0], pA1); } } }
;         bias_add<DIFF>(pA0, pA1, bm, tab, ix);
;         if constexpr (!STAT) rowmax_decide<DIFF, true>(pA0, pA1, m_reg, alA, moved, bm, tab, ix); else moved = false;
; #pragma unroll
;         for (int r = 0; r < 16; ++r) { pA0[r] = __builtin_amdgcn_exp2f(pA0[r]); pA1[r] = __builtin_amdgcn_exp2f(pA1[r]); }
.LBB0_588:
	v_readlane_b32 s4, v254, 45
	v_readlane_b32 s5, v254, 46
	s_lshl_b32 s8, s64, 14
	s_nop 3
	global_load_dword v1, v0, s[4:5]
	s_lshl_b32 s4, s64, 12
	s_add_i32 s9, s4, 0x6000
	s_cmp_lt_u32 s64, 2
	s_cselect_b64 s[4:5], -1, 0
	s_and_b64 s[6:7], s[4:5], exec
	s_mov_b32 s6, 0x42200000
	s_cselect_b32 s48, 0x100, 64
	s_cselect_b32 s14, s8, s9
	s_lshl_b32 s42, s63, 8
	s_waitcnt vmcnt(0)
	v_cmp_nge_f32_e32 vcc, s6, v1
	s_cbranch_vccnz .LBB0_595
	v_mov_b32_e32 v42, v230
	s_lshl_b64 s[6:7], s[14:15], 3
	v_readfirstlane_b32 s9, v42
	s_ashr_i32 s8, s9, 6
	s_lshl_b32 s43, s8, 5
	s_add_i32 s43, s43, s42
	s_and_b64 s[12:13], s[4:5], exec
	s_mov_b32 s73, s15
	s_cselect_b32 s40, 14, 12
	s_lshl_b64 s[12:13], s[72:73], s40
	s_add_u32 s6, s6, s12
	s_addc_u32 s7, s7, s13
	s_ashr_i32 s12, s43, 31
	s_add_u32 s6, s6, s43
	s_addc_u32 s7, s7, s12
	s_lshl_b64 s[6:7], s[6:7], 7
	s_add_u32 s12, s92, s6
	s_addc_u32 s13, s93, s7
	s_lshr_b32 s6, s72, 2
	s_mov_b32 s7, s15
	s_lshl_b64 s[6:7], s[6:7], s40
	s_lshl_b64 s[40:41], s[14:15], 8
	s_lshl_b64 s[6:7], s[6:7], 7
	s_add_u32 s6, s40, s6
	s_addc_u32 s7, s41, s7
	v_readlane_b32 s16, v254, 47
	s_add_u32 s40, s16, s6
	v_readlane_b32 s16, v254, 48
	s_addc_u32 s41, s16, s7
	v_readlane_b32 s16, v254, 49
	v_and_b32_e32 v133, 63, v42
	s_add_u32 s6, s16, s6
	v_readlane_b32 s16, v254, 50
	v_lshlrev_b32_e32 v43, 4, v133
	s_addc_u32 s7, s16, s7
	s_lshl_b32 s47, s8, 10
	v_or_b32_e32 v134, s47, v43
	s_add_i32 s46, s47, s65
	s_add_i32 s47, s47, 0
	s_add_u32 s50, s40, 0x2000
	s_addc_u32 s51, s41, 0
	s_add_u32 s54, s6, 0x2000
	s_addc_u32 s55, s7, 0
	s_add_u32 s56, s40, 0x4000
	v_and_b32_e32 v132, 31, v42
	s_addc_u32 s57, s41, 0
	s_barrier
	s_mov_b32 s8, m0
	s_mov_b32 m0, s46
	s_nop 0
	global_load_lds_dwordx4 v134, s[40:41]
	s_mov_b32 m0, s8
	s_add_u32 s58, s6, 0x4000
	v_lshlrev_b32_e32 v2, 7, v132
	v_mov_b32_e32 v3, v0
	s_mov_b32 s8, m0
	s_mov_b32 m0, s47
	s_nop 0
	global_load_lds_dwordx4 v134, s[6:7]
	s_mov_b32 m0, s8
	s_addc_u32 s59, s7, 0
	v_lshl_add_u64 v[2:3], s[12:13], 0, v[2:3]
	s_add_i32 s8, s47, 0x16000
	s_mov_b32 s12, m0
	s_mov_b32 m0, s8
	s_nop 0
	global_load_lds_dwordx4 v134, s[50:51]
	s_mov_b32 m0, s12
	v_bfe_u32 v150, v42, 5, 1
	s_add_i32 s8, s47, 0x4000
	s_mov_b32 s12, m0
	s_mov_b32 m0, s8
	s_nop 0
	global_load_lds_dwordx4 v134, s[54:55]
	s_mov_b32 m0, s12
	v_lshlrev_b32_e32 v148, 4, v150
	v_mov_b32_e32 v149, v0
	s_add_i32 s8, s47, 0x18000
	s_mov_b32 s12, m0
	s_mov_b32 m0, s8
	s_nop 0
	global_load_lds_dwordx4 v134, s[56:57]
	s_mov_b32 m0, s12
	v_lshl_add_u64 v[6:7], v[2:3], 0, v[148:149]
	s_add_i32 s8, s47, 0x8000
	s_mov_b32 s12, m0
	s_mov_b32 m0, s8
	s_nop 0
	global_load_lds_dwordx4 v134, s[58:59]
	s_mov_b32 m0, s12
	global_load_dwordx4 v[124:127], v[6:7], off
	global_load_dwordx4 v[120:123], v[6:7], off offset:32
	global_load_dwordx4 v[116:119], v[6:7], off offset:64
	global_load_dwordx4 v[112:115], v[6:7], off offset:96
	v_mov_b32_e32 v2, v0
	v_mov_b32_e32 v3, v0
	v_mov_b32_e32 v4, v0
	v_mov_b32_e32 v5, v0
	v_mov_b32_e32 v6, v0
	v_mov_b32_e32 v7, v0
	v_mov_b32_e32 v8, v0
	v_mov_b32_e32 v9, v0
	v_mov_b32_e32 v10, v0
	v_mov_b32_e32 v11, v0
	v_mov_b32_e32 v12, v0
	v_mov_b32_e32 v13, v0
	v_mov_b32_e32 v14, v0
	v_mov_b32_e32 v15, v0
	v_mov_b32_e32 v1, v0
	v_mov_b64_e32 v[16:17], v[14:15]
	v_mov_b64_e32 v[14:15], v[12:13]
	v_mov_b64_e32 v[12:13], v[10:11]
	v_mov_b64_e32 v[10:11], v[8:9]
	v_mov_b64_e32 v[8:9], v[6:7]
	v_mov_b64_e32 v[6:7], v[4:5]
	v_mov_b64_e32 v[4:5], v[2:3]
	v_mov_b64_e32 v[2:3], v[0:1]
	v_lshlrev_b32_e32 v1, 10, v150
	v_lshlrev_b32_e32 v18, 4, v132
	v_add3_u32 v135, s65, v1, v18
	s_waitcnt vmcnt(0) lgkmcnt(0)
	s_barrier
	ds_read_b128 v[2:5], v135
	ds_read_b128 v[18:21], v135 offset:512
	ds_read_b128 v[34:37], v135 offset:2048
	ds_read_b128 v[38:41], v135 offset:2560
	s_add_i32 s50, s48, -1
	v_lshlrev_b32_e32 v1, 1, v42
	v_lshlrev_b32_e32 v42, 3, v133
	s_add_u32 s6, s6, 0x8000
	s_addc_u32 s7, s7, 0
	v_and_b32_e32 v1, 32, v1
	s_add_u32 s40, s40, 0x8000
	s_mov_b32 s49, 4
	s_mov_b32 s8, 1
	s_mov_b32 s54, 0
	s_addc_u32 s41, s41, 0
	s_waitcnt vmcnt(3) lgkmcnt(3)
	v_mfma_f32_32x32x16_bf16 v[2:17], v[2:5], v[124:127], 0
	s_waitcnt lgkmcnt(2)
	v_mfma_f32_32x32x16_bf16 v[18:33], v[18:21], v[124:127], 0
	s_waitcnt vmcnt(2) lgkmcnt(1)
	v_mfma_f32_32x32x16_bf16 v[2:17], v[34:37], v[120:123], v[2:17]
	s_waitcnt lgkmcnt(0)
	v_mfma_f32_32x32x16_bf16 v[18:33], v[38:41], v[120:123], v[18:33]
	ds_read_b128 v[34:37], v135 offset:4096
	ds_read_b128 v[38:41], v135 offset:4608
	s_waitcnt vmcnt(1) lgkmcnt(1)
	v_mfma_f32_32x32x16_bf16 v[2:17], v[34:37], v[116:119], v[2:17]
	ds_read_b128 v[34:37], v135 offset:6144
	s_waitcnt lgkmcnt(1)
	v_mfma_f32_32x32x16_bf16 v[18:33], v[38:41], v[116:119], v[18:33]
	ds_read_b128 v[38:41], v135 offset:6656
	s_waitcnt vmcnt(0) lgkmcnt(1)
	v_mfma_f32_32x32x16_bf16 v[2:17], v[34:37], v[112:115], v[2:17]
	v_and_b32_e32 v34, 24, v42
	v_and_b32_e32 v35, 0xc0, v43
	v_and_b32_e32 v36, 0x100, v42
	v_add3_u32 v34, 0, v34, v35
	v_add3_u32 v1, v34, v1, v36
	s_nop 6
	v_exp_f32_e32 v64, v2
	s_waitcnt lgkmcnt(0)
	v_mfma_f32_32x32x16_bf16 v[18:33], v[38:41], v[112:115], v[18:33]
	v_exp_f32_e32 v65, v3
	v_exp_f32_e32 v66, v4
	v_exp_f32_e32 v67, v5
	v_exp_f32_e32 v68, v6
	v_exp_f32_e32 v69, v7
	v_exp_f32_e32 v70, v8
	v_exp_f32_e32 v71, v9
	s_nop 4
	v_exp_f32_e32 v48, v18
	v_exp_f32_e32 v49, v19
	v_exp_f32_e32 v50, v20
	v_exp_f32_e32 v51, v21
	v_exp_f32_e32 v52, v22
	v_exp_f32_e32 v53, v23
	v_exp_f32_e32 v54, v24
	v_exp_f32_e32 v55, v25
	v_exp_f32_e32 v56, v26
	v_exp_f32_e32 v57, v27
	v_exp_f32_e32 v58, v28
	v_exp_f32_e32 v59, v29
	v_exp_f32_e32 v60, v30
	v_exp_f32_e32 v61, v31
	v_exp_f32_e32 v62, v32
	v_exp_f32_e32 v63, v33
	v_exp_f32_e32 v72, v10
	v_exp_f32_e32 v73, v11
	v_exp_f32_e32 v74, v12
	v_exp_f32_e32 v75, v13
	v_exp_f32_e32 v76, v14
	v_exp_f32_e32 v77, v15
	v_exp_f32_e32 v78, v16
	v_exp_f32_e32 v79, v17
	v_mov_b32_e32 v14, 0
	v_mov_b32_e32 v144, 0
	v_mov_b32_e32 v145, 0
	v_mov_b32_e32 v146, 0
	v_mov_b32_e32 v147, 0
	v_and_b32_e32 v140, 15, v230
	v_bfe_u32 v141, v230, 4, 1
	v_mov_b32_e32 v142, 0x3f803f80
	v_cmp_eq_u32_e64 s[98:99], v140, v141
	s_nop 1
	v_cndmask_b32_e64 v140, 0, v142, s[98:99]
	v_mov_b32_e32 v141, v140
	v_mov_b32_e32 v142, v140
	v_mov_b32_e32 v143, v140
	v_mov_b32_e32 v16, 0
	v_mov_b32_e32 v17, v14
	v_mov_b32_e32 v18, v14
	v_mov_b32_e32 v19, v14
	v_mov_b32_e32 v20, v14
	v_mov_b32_e32 v21, v14
	v_mov_b32_e32 v22, v14
	v_mov_b32_e32 v23, v14
	v_mov_b32_e32 v24, v14
	v_mov_b32_e32 v25, v14
	v_mov_b32_e32 v26, v14
	v_mov_b32_e32 v27, v14
	v_mov_b32_e32 v28, v14
	v_mov_b32_e32 v29, v14
	v_mov_b32_e32 v30, v14
	v_mov_b32_e32 v31, v14
	v_mov_b32_e32 v32, 0
	v_mov_b32_e32 v33, v14
	v_mov_b32_e32 v34, v14
	v_mov_b32_e32 v35, v14
	v_mov_b32_e32 v36, v14
	v_mov_b32_e32 v37, v14
	v_mov_b32_e32 v38, v14
	v_mov_b32_e32 v39, v14
	v_mov_b32_e32 v40, v14
	v_mov_b32_e32 v41, v14
	v_mov_b32_e32 v42, v14
	v_mov_b32_e32 v43, v14
	v_mov_b32_e32 v44, v14
	v_mov_b32_e32 v45, v14
	v_mov_b32_e32 v46, v14
	v_mov_b32_e32 v47, v14
	s_branch .LBB0_591
.LBB0_590:
	s_waitcnt lgkmcnt(2)
	v_mfma_f32_32x32x16_bf16 v[16:31], v[128:131], v[48:51], v[16:31]
	ds_read_b64_tr_b16 v[56:57], v15 offset:2048
	ds_read_b64_tr_b16 v[58:59], v15 offset:3072
	v_mfma_f32_16x16x32_bf16 v[144:147], v[2:5], v[140:143], v[144:147]
	v_exp_f32_e32 v96, v96
	v_exp_f32_e32 v97, v97
	v_exp_f32_e32 v98, v98
	v_exp_f32_e32 v99, v99
	s_waitcnt lgkmcnt(2)
	v_mfma_f32_32x32x16_bf16 v[32:47], v[128:131], v[52:55], v[32:47]
	ds_read_b64_tr_b16 v[48:49], v15 offset:2560
	ds_read_b64_tr_b16 v[50:51], v15 offset:3584
	v_exp_f32_e32 v100, v100
	v_exp_f32_e32 v101, v101
	v_exp_f32_e32 v102, v102
	v_exp_f32_e32 v103, v103
	s_waitcnt lgkmcnt(2)
	v_mfma_f32_32x32x16_bf16 v[16:31], v[10:13], v[56:59], v[16:31]
	ds_read_b64_tr_b16 v[52:53], v15 offset:4096
	ds_read_b64_tr_b16 v[54:55], v15 offset:5120
	v_exp_f32_e32 v104, v104
	v_exp_f32_e32 v105, v105
	v_exp_f32_e32 v106, v106
	v_exp_f32_e32 v107, v107
	s_waitcnt lgkmcnt(2)
	v_mfma_f32_32x32x16_bf16 v[32:47], v[10:13], v[48:51], v[32:47]
	ds_read_b64_tr_b16 v[56:57], v15 offset:4608
	ds_read_b64_tr_b16 v[58:59], v15 offset:5632
	v_exp_f32_e32 v108, v108
	v_exp_f32_e32 v109, v109
	v_exp_f32_e32 v110, v110
	v_exp_f32_e32 v111, v111
	s_waitcnt lgkmcnt(2)
	v_mfma_f32_32x32x16_bf16 v[16:31], v[6:9], v[52:55], v[16:31]
	ds_read_b64_tr_b16 v[10:11], v15 offset:6144
	ds_read_b64_tr_b16 v[12:13], v15 offset:7168
	v_exp_f32_e32 v80, v80
	v_exp_f32_e32 v81, v81
	v_exp_f32_e32 v82, v82
	v_exp_f32_e32 v83, v83
	s_waitcnt lgkmcnt(2)
	v_mfma_f32_32x32x16_bf16 v[32:47], v[6:9], v[56:59], v[32:47]
	ds_read_b64_tr_b16 v[48:49], v15 offset:6656
	ds_read_b64_tr_b16 v[50:51], v15 offset:7680
	v_exp_f32_e32 v84, v84
	v_exp_f32_e32 v85, v85
	v_exp_f32_e32 v86, v86
	v_exp_f32_e32 v87, v87
	s_waitcnt lgkmcnt(2)
	v_mfma_f32_32x32x16_bf16 v[16:31], v[2:5], v[10:13], v[16:31]
	v_exp_f32_e32 v88, v88
	v_exp_f32_e32 v89, v89
	v_exp_f32_e32 v90, v90
	v_exp_f32_e32 v91, v91
	s_waitcnt lgkmcnt(0)
	v_mfma_f32_32x32x16_bf16 v[32:47], v[2:5], v[48:51], v[32:47]
	v_exp_f32_e32 v92, v92
	v_exp_f32_e32 v93, v93
	v_exp_f32_e32 v94, v94
	v_exp_f32_e32 v95, v95
	s_add_i32 s12, s8, -4
	s_add_i32 s13, s8, 1
	s_cmp_gt_i32 s8, 3
	s_cselect_b32 s12, s12, s13
	v_lshl_add_u32 v6, s12, 13, v135
	ds_read_b128 v[2:5], v6
	ds_read_b128 v[6:9], v6 offset:512
	s_cmp_lg_u32 s8, 4
	s_cselect_b32 s54, s13, 0
	v_lshl_add_u32 v15, s54, 13, v135
	v_lshl_add_u32 v128, s8, 14, v1
	s_waitcnt lgkmcnt(1)
	v_mfma_f32_32x32x16_bf16 v[64:79], v[2:5], v[124:127], 0
	ds_read_b128 v[10:13], v15 offset:2048
	v_cvt_pk_bf16_f32 v2, v96, v97
	v_cvt_pk_bf16_f32 v3, v98, v99
	s_nop 0
	ds_read_b128 v[96:99], v15 offset:2560
	v_cvt_pk_bf16_f32 v4, v100, v101
	s_waitcnt lgkmcnt(2)
	v_mfma_f32_32x32x16_bf16 v[48:63], v[6:9], v[124:127], 0
	v_cvt_pk_bf16_f32 v5, v102, v103
	s_waitcnt lgkmcnt(1)
	v_mfma_f32_32x32x16_bf16 v[64:79], v[10:13], v[120:123], v[64:79]
	ds_read_b128 v[6:9], v15 offset:4096
	v_mfma_f32_16x16x32_bf16 v[144:147], v[2:5], v[140:143], v[144:147]
	v_cvt_pk_bf16_f32 v10, v104, v105
	v_cvt_pk_bf16_f32 v11, v106, v107
	s_waitcnt lgkmcnt(1)
	v_mfma_f32_32x32x16_bf16 v[48:63], v[96:99], v[120:123], v[48:63]
	ds_read_b128 v[100:103], v15 offset:4608
	v_cvt_pk_bf16_f32 v12, v108, v109
	v_cvt_pk_bf16_f32 v13, v110, v111
	s_waitcnt lgkmcnt(1)
	v_mfma_f32_32x32x16_bf16 v[64:79], v[6:9], v[116:119], v[64:79]
	ds_read_b128 v[96:99], v15 offset:6144
	v_mfma_f32_16x16x32_bf16 v[144:147], v[10:13], v[140:143], v[144:147]
	v_cvt_pk_bf16_f32 v6, v80, v81
	v_cvt_pk_bf16_f32 v7, v82, v83
	s_waitcnt lgkmcnt(1)
	v_mfma_f32_32x32x16_bf16 v[48:63], v[100:103], v[116:119], v[48:63]
	ds_read_b128 v[80:83], v15 offset:6656
	v_cvt_pk_bf16_f32 v8, v84, v85
	v_cvt_pk_bf16_f32 v9, v86, v87
	s_waitcnt lgkmcnt(1)
	v_mfma_f32_32x32x16_bf16 v[64:79], v[96:99], v[112:115], v[64:79]
	v_mfma_f32_16x16x32_bf16 v[144:147], v[6:9], v[140:143], v[144:147]
	v_cvt_pk_bf16_f32 v84, v88, v89
	v_cvt_pk_bf16_f32 v85, v90, v91
	ds_read_b64_tr_b16 v[88:89], v128
	ds_read_b64_tr_b16 v[90:91], v128 offset:1024
	s_waitcnt lgkmcnt(2)
	v_mfma_f32_32x32x16_bf16 v[48:63], v[80:83], v[112:115], v[48:63]
	v_cvt_pk_bf16_f32 v86, v92, v93
	v_cvt_pk_bf16_f32 v87, v94, v95
	ds_read_b64_tr_b16 v[80:81], v128 offset:512
	ds_read_b64_tr_b16 v[82:83], v128 offset:1536
	s_waitcnt lgkmcnt(2)
	v_mfma_f32_32x32x16_bf16 v[16:31], v[2:5], v[88:91], v[16:31]
	ds_read_b64_tr_b16 v[92:93], v128 offset:2048
	ds_read_b64_tr_b16 v[94:95], v128 offset:3072
	v_mfma_f32_16x16x32_bf16 v[144:147], v[84:87], v[140:143], v[144:147]
	v_exp_f32_e32 v64, v64
	v_exp_f32_e32 v65, v65
	v_exp_f32_e32 v66, v66
	v_exp_f32_e32 v67, v67
	s_waitcnt lgkmcnt(2)
	v_mfma_f32_32x32x16_bf16 v[32:47], v[2:5], v[80:83], v[32:47]
	ds_read_b64_tr_b16 v[88:89], v128 offset:2560
	ds_read_b64_tr_b16 v[90:91], v128 offset:3584
	v_exp_f32_e32 v68, v68
	v_exp_f32_e32 v69, v69
	v_exp_f32_e32 v70, v70
	v_exp_f32_e32 v71, v71
	s_waitcnt lgkmcnt(2)
	v_mfma_f32_32x32x16_bf16 v[16:31], v[10:13], v[92:95], v[16:31]
	ds_read_b64_tr_b16 v[2:3], v128 offset:4096
	ds_read_b64_tr_b16 v[4:5], v128 offset:5120
	v_exp_f32_e32 v72, v72
	v_exp_f32_e32 v73, v73
	v_exp_f32_e32 v74, v74
	v_exp_f32_e32 v75, v75
	s_waitcnt lgkmcnt(2)
	v_mfma_f32_32x32x16_bf16 v[32:47], v[10:13], v[88:91], v[32:47]
	ds_read_b64_tr_b16 v[80:81], v128 offset:4608
	ds_read_b64_tr_b16 v[82:83], v128 offset:5632
	v_exp_f32_e32 v76, v76
	v_exp_f32_e32 v77, v77
	v_exp_f32_e32 v78, v78
	v_exp_f32_e32 v79, v79
	s_waitcnt lgkmcnt(2)
	v_mfma_f32_32x32x16_bf16 v[16:31], v[6:9], v[2:5], v[16:31]
	ds_read_b64_tr_b16 v[10:11], v128 offset:6144
	ds_read_b64_tr_b16 v[12:13], v128 offset:7168
	v_exp_f32_e32 v48, v48
	v_exp_f32_e32 v49, v49
	v_exp_f32_e32 v50, v50
	v_exp_f32_e32 v51, v51
	s_waitcnt lgkmcnt(2)
	v_mfma_f32_32x32x16_bf16 v[32:47], v[6:9], v[80:83], v[32:47]
	ds_read_b64_tr_b16 v[2:3], v128 offset:6656
	ds_read_b64_tr_b16 v[4:5], v128 offset:7680
	v_exp_f32_e32 v52, v52
	v_exp_f32_e32 v53, v53
	v_exp_f32_e32 v54, v54
	v_exp_f32_e32 v55, v55
	s_waitcnt lgkmcnt(2)
	v_mfma_f32_32x32x16_bf16 v[16:31], v[84:87], v[10:13], v[16:31]
	v_exp_f32_e32 v56, v56
	v_exp_f32_e32 v57, v57
	v_exp_f32_e32 v58, v58
	v_exp_f32_e32 v59, v59
	s_waitcnt lgkmcnt(0)
	v_mfma_f32_32x32x16_bf16 v[32:47], v[84:87], v[2:5], v[32:47]
	v_exp_f32_e32 v60, v60
	v_exp_f32_e32 v61, v61
	v_exp_f32_e32 v62, v62
	v_exp_f32_e32 v63, v63
	s_add_i32 s8, s54, 1
	s_cmp_lg_u32 s54, 4
	s_cselect_b32 s8, s8, 0
	s_add_u32 s6, s6, 0x4000
	s_addc_u32 s7, s7, 0
	s_add_u32 s40, s40, 0x4000
	s_waitcnt vmcnt(0) lgkmcnt(0)
	s_barrier
	s_addc_u32 s41, s41, 0
	s_add_i32 s49, s49, 2
	s_cmp_lt_u32 s51, s50
	s_cbranch_scc0 .LBB0_596
.LBB0_591:
	v_lshl_add_u32 v136, s8, 13, v135
	ds_read_b128 v[2:5], v136
	ds_read_b128 v[6:9], v136 offset:512
	s_lshl_b32 s12, s54, 14
	v_add_u32_e32 v15, s12, v1
	s_waitcnt lgkmcnt(1)
	v_mfma_f32_32x32x16_bf16 v[96:111], v[2:5], v[124:127], 0
	ds_read_b128 v[10:13], v136 offset:2048
	v_cvt_pk_bf16_f32 v128, v64, v65
	v_cvt_pk_bf16_f32 v129, v66, v67
	s_waitcnt lgkmcnt(1)
	v_mfma_f32_32x32x16_bf16 v[80:95], v[6:9], v[124:127], 0
	ds_read_b128 v[2:5], v136 offset:2560
	v_cvt_pk_bf16_f32 v130, v68, v69
	v_cvt_pk_bf16_f32 v131, v70, v71
	s_waitcnt lgkmcnt(1)
	v_mfma_f32_32x32x16_bf16 v[96:111], v[10:13], v[120:123], v[96:111]
	ds_read_b128 v[6:9], v136 offset:4096
	v_mfma_f32_16x16x32_bf16 v[144:147], v[128:131], v[140:143], v[144:147]
	v_cvt_pk_bf16_f32 v10, v72, v73
	v_cvt_pk_bf16_f32 v11, v74, v75
	s_waitcnt lgkmcnt(1)
	v_mfma_f32_32x32x16_bf16 v[80:95], v[2:5], v[120:123], v[80:95]
	ds_read_b128 v[64:67], v136 offset:4608
	v_cvt_pk_bf16_f32 v12, v76, v77
	v_cvt_pk_bf16_f32 v13, v78, v79
	s_waitcnt lgkmcnt(1)
	v_mfma_f32_32x32x16_bf16 v[96:111], v[6:9], v[116:119], v[96:111]
	ds_read_b128 v[2:5], v136 offset:6144
	v_mfma_f32_16x16x32_bf16 v[144:147], v[10:13], v[140:143], v[144:147]
	v_cvt_pk_bf16_f32 v6, v48, v49
	v_cvt_pk_bf16_f32 v7, v50, v51
	s_waitcnt lgkmcnt(1)
	v_mfma_f32_32x32x16_bf16 v[80:95], v[64:67], v[116:119], v[80:95]
	ds_read_b128 v[68:71], v136 offset:6656
	v_cvt_pk_bf16_f32 v8, v52, v53
	v_cvt_pk_bf16_f32 v9, v54, v55
	s_waitcnt lgkmcnt(1)
	v_mfma_f32_32x32x16_bf16 v[96:111], v[2:5], v[112:115], v[96:111]
	v_mfma_f32_16x16x32_bf16 v[144:147], v[6:9], v[140:143], v[144:147]
	v_cvt_pk_bf16_f32 v2, v56, v57
	v_cvt_pk_bf16_f32 v3, v58, v59
	ds_read_b64_tr_b16 v[48:49], v15
	ds_read_b64_tr_b16 v[50:51], v15 offset:1024
	s_waitcnt lgkmcnt(2)
	v_mfma_f32_32x32x16_bf16 v[80:95], v[68:71], v[112:115], v[80:95]
	v_cvt_pk_bf16_f32 v4, v60, v61
	v_cvt_pk_bf16_f32 v5, v62, v63
	ds_read_b64_tr_b16 v[52:53], v15 offset:512
	ds_read_b64_tr_b16 v[54:55], v15 offset:1536
	s_add_i32 s51, s49, -1
	s_cmp_ge_u32 s51, s48
	s_cbranch_scc1 .LBB0_593
	s_add_u32 s12, s40, 0xffffe000
	s_addc_u32 s13, s41, -1
	s_cmp_gt_i32 s8, 2
	s_cselect_b32 s54, -3, 2
	s_add_i32 s54, s54, s8
	s_lshl_b32 s55, s54, 13
	s_add_i32 s55, s55, s46
	s_mov_b32 s56, m0
	s_mov_b32 m0, s55
	s_nop 0
	global_load_lds_dwordx4 v134, s[12:13]
	s_mov_b32 m0, s56
	s_add_u32 s12, s6, 0xffffe000
	s_addc_u32 s13, s7, -1
	s_lshl_b32 s54, s54, 14
	s_add_i32 s54, s54, s47
	s_mov_b32 s55, m0
	s_mov_b32 m0, s54
	s_nop 0
	global_load_lds_dwordx4 v134, s[12:13]
	s_mov_b32 m0, s55

.LBB0_596:
	s_and_b32 s6, s9, 0x3fffffc0
	s_lshl_b32 s6, s6, 2
	s_add_i32 s6, s6, 0
	s_add_i32 s49, s6, 0x1e000
	v_cmp_gt_u32_e32 vcc, 32, v133
	v_lshl_add_u32 v15, s8, 13, v135
	ds_read_b128 v[2:5], v15
	ds_read_b128 v[6:9], v15 offset:512
	v_lshl_add_u32 v128, s54, 14, v1
	ds_read_b128 v[10:13], v15 offset:2048
	s_waitcnt lgkmcnt(2)
	v_mfma_f32_32x32x16_bf16 v[80:95], v[2:5], v[124:127], 0
	v_add_f32_e32 v4, 0, v65
	v_add_f32_e32 v96, v67, v4
	v_add_f32_e32 v4, 0, v64
	v_add_f32_e32 v97, v66, v4
	v_cvt_pk_bf16_f32 v2, v64, v65
	v_cvt_pk_bf16_f32 v3, v66, v67
	ds_read_b128 v[64:67], v15 offset:2560
	v_cvt_pk_bf16_f32 v4, v68, v69
	v_add_f32_e32 v69, v69, v96
	v_add_f32_e32 v68, v68, v97
	v_add_f32_e32 v69, v71, v69
	v_add_f32_e32 v68, v70, v68
	v_cvt_pk_bf16_f32 v5, v70, v71
	s_waitcnt lgkmcnt(2)
	v_mfma_f32_32x32x16_bf16 v[96:111], v[6:9], v[124:127], 0
	ds_read_b128 v[6:9], v15 offset:4096
	s_waitcnt lgkmcnt(2)
	v_mfma_f32_32x32x16_bf16 v[80:95], v[10:13], v[120:123], v[80:95]
	v_add_f32_e32 v12, v73, v69
	v_cvt_pk_bf16_f32 v10, v72, v73
	v_add_f32_e32 v73, v75, v12
	v_add_f32_e32 v12, v72, v68
	v_add_f32_e32 v72, v74, v12
	v_cvt_pk_bf16_f32 v11, v74, v75
	ds_read_b128 v[68:71], v15 offset:4608
	s_waitcnt lgkmcnt(2)
	v_mfma_f32_32x32x16_bf16 v[96:111], v[64:67], v[120:123], v[96:111]
	v_add_f32_e32 v64, v77, v73
	v_add_f32_e32 v74, v79, v64
	v_add_f32_e32 v64, v76, v72
	v_add_f32_e32 v75, v78, v64
	v_cvt_pk_bf16_f32 v12, v76, v77
	v_cvt_pk_bf16_f32 v13, v78, v79
	ds_read_b128 v[64:67], v15 offset:6144
	s_waitcnt lgkmcnt(2)
	v_mfma_f32_32x32x16_bf16 v[80:95], v[6:9], v[116:119], v[80:95]
	v_add_f32_e32 v6, v49, v74
	v_cvt_pk_bf16_f32 v72, v48, v49
	v_add_f32_e32 v49, v51, v6
	v_add_f32_e32 v6, v48, v75
	v_add_f32_e32 v48, v50, v6
	v_cvt_pk_bf16_f32 v73, v50, v51
	ds_read_b128 v[6:9], v15 offset:6656
	v_add_f32_e32 v15, v53, v49
	v_add_f32_e32 v48, v52, v48
	v_add_f32_e32 v15, v55, v15
	v_add_f32_e32 v50, v54, v48
	s_waitcnt lgkmcnt(2)
	v_mfma_f32_32x32x16_bf16 v[96:111], v[68:71], v[116:119], v[96:111]
	v_cvt_pk_bf16_f32 v74, v52, v53
	v_cvt_pk_bf16_f32 v75, v54, v55
	s_nop 0
	v_add_f32_e32 v15, v57, v15
	v_add_f32_e32 v50, v56, v50
	v_cvt_pk_bf16_f32 v48, v56, v57
	v_add_f32_e32 v15, v59, v15
	v_add_f32_e32 v56, v58, v50
	v_cvt_pk_bf16_f32 v49, v58, v59
	ds_read_b64_tr_b16 v[52:53], v128
	ds_read_b64_tr_b16 v[54:55], v128 offset:1024
	s_waitcnt lgkmcnt(3)
	v_mfma_f32_32x32x16_bf16 v[80:95], v[64:67], v[112:115], v[80:95]
	s_waitcnt lgkmcnt(2)
	v_mfma_f32_32x32x16_bf16 v[96:111], v[6:9], v[112:115], v[96:111]
	v_add_f32_e32 v6, v61, v15
	v_add_f32_e32 v7, v60, v56
	v_add_f32_e32 v6, v63, v6
	v_add_f32_e32 v7, v62, v7
	v_cvt_pk_bf16_f32 v50, v60, v61
	v_cvt_pk_bf16_f32 v51, v62, v63
	ds_read_b64_tr_b16 v[56:57], v128 offset:512
	ds_read_b64_tr_b16 v[58:59], v128 offset:1536
	s_waitcnt lgkmcnt(2)
	v_mfma_f32_32x32x16_bf16 v[16:31], v[2:5], v[52:55], v[16:31]
	ds_read_b64_tr_b16 v[60:61], v128 offset:2048
	ds_read_b64_tr_b16 v[62:63], v128 offset:3072
	v_exp_f32_e32 v80, v80
	v_exp_f32_e32 v81, v81
	v_exp_f32_e32 v82, v82
	v_exp_f32_e32 v83, v83
	v_add_f32_e32 v6, v7, v6
	s_waitcnt lgkmcnt(2)
	v_mfma_f32_32x32x16_bf16 v[32:47], v[2:5], v[56:59], v[32:47]
	ds_read_b64_tr_b16 v[52:53], v128 offset:2560
	ds_read_b64_tr_b16 v[54:55], v128 offset:3584
	v_exp_f32_e32 v84, v84
	v_exp_f32_e32 v85, v85
	v_exp_f32_e32 v86, v86
	v_exp_f32_e32 v87, v87
	s_waitcnt lgkmcnt(2)
	v_mfma_f32_32x32x16_bf16 v[16:31], v[10:13], v[60:63], v[16:31]
	ds_read_b64_tr_b16 v[2:3], v128 offset:4096
	ds_read_b64_tr_b16 v[4:5], v128 offset:5120
	v_exp_f32_e32 v88, v88
	v_exp_f32_e32 v89, v89
	v_exp_f32_e32 v90, v90
	v_exp_f32_e32 v91, v91
	s_waitcnt lgkmcnt(2)
	v_mfma_f32_32x32x16_bf16 v[32:47], v[10:13], v[52:55], v[32:47]
	ds_read_b64_tr_b16 v[56:57], v128 offset:4608
	ds_read_b64_tr_b16 v[58:59], v128 offset:5632
	v_exp_f32_e32 v92, v92
	v_exp_f32_e32 v93, v93
	v_exp_f32_e32 v94, v94
	v_exp_f32_e32 v95, v95
	s_waitcnt lgkmcnt(2)
	v_mfma_f32_32x32x16_bf16 v[16:31], v[72:75], v[2:5], v[16:31]
	ds_read_b64_tr_b16 v[8:9], v128 offset:6144
	ds_read_b64_tr_b16 v[10:11], v128 offset:7168
	v_exp_f32_e32 v96, v96
	v_exp_f32_e32 v97, v97
	v_exp_f32_e32 v98, v98
	v_exp_f32_e32 v99, v99
	s_waitcnt lgkmcnt(2)
; #define LAS __attribute__((address_space(3)))
; __device__ __forceinline__ int crow(int r, int hi) { return (r & 3) + 8 * (r >> 2) + 4 * hi; }
; __device__ __forceinline__ int crow(int r, int hi) { return (r & 3) + 8 * (r >> 2) + 4 * hi; }
; #define PKW(P, B) cvtpk(P[B], P[B + 1])
; #define MFMA32(a, b, c) __builtin_amdgcn_mfma_f32_32x32x16_bf16(a, b, c, 0, 0, 0)
; #define VRD(g) do { const int o_ = ((g) % NCB) * 512 + (2 * ((g) / NCB)) * NCB * 512; vl[(g) % 3] = tr_rd(vp_ + o_); vh[(g) % 3] = tr_rd(vp_ + o_ + NCB * 512); } while (0)
; template <int NCB, bool DIFF, bool STAT>
; __device__ __forceinline__ void attn_unit(LAS char* lds, const Params& P, int s, int head, int qb, float sref) {
;     ...
;         { const LAS char* vp_ = vp0 + sl_prev * SHM_V; s16x4 vl[3], vh[3];
;           float s0_ = 0.f;
; #pragma unroll
;           for (int r = 0; r < 16; ++r) s0_ += pB0[r] + pB1[r];
;           if constexpr (STAT) l_reg += s0_; else l_reg = l_reg * alB + s0_;
;           pw[0] = (u32x4){PKW(pB0, 0), PKW(pB0, 2), PKW(pB0, 4), PKW(pB0, 6)}; pw[1] = (u32x4){PKW(pB0, 8), PKW(pB0, 10), PKW(pB0, 12), PKW(pB0, 14)};
;           pw[2] = (u32x4){PKW(pB1, 0), PKW(pB1, 2), PKW(pB1, 4), PKW(pB1, 6)}; pw[3] = (u32x4){PKW(pB1, 8), PKW(pB1, 10), PKW(pB1, 12), PKW(pB1, 14)};
; #pragma unroll
;           for (int g = 0; g < NG; ++g) { VRD(g); o[g % NCB] = MFMA32(__builtin_bit_cast(bf16x8, pw[g / NCB]), PKV(vl[g % 3], vh[g % 3]), o[g % NCB]); } }
;     ...
;         { auto rr = __builtin_amdgcn_permlane32_swap(__float_as_uint(l_reg), __float_as_uint(l_reg), false, false); l_reg = __uint_as_float(rr[0]) + __uint_as_float(rr[1]); }
;         if (hi == 0) li_l[r32] = l_reg; asm volatile("s_waitcnt lgkmcnt(0)" ::: "memory");
;         float rli[16];
; #pragma unroll
;         for (int r = 0; r < 16; ++r) rli[r] = __builtin_amdgcn_rcpf(li_l[crow(r, hi)]);
;         bf16* mixw = (bf16*)(ws + WS_MIX) + (size_t)(sb + qw) * DM;
	v_mfma_f32_32x32x16_bf16 v[32:47], v[72:75], v[56:59], v[32:47]
	ds_read_b64_tr_b16 v[2:3], v128 offset:6656
	ds_read_b64_tr_b16 v[4:5], v128 offset:7680
	v_exp_f32_e32 v100, v100
	v_exp_f32_e32 v101, v101
	v_exp_f32_e32 v102, v102
	v_exp_f32_e32 v103, v103
	s_waitcnt lgkmcnt(2)
	v_mfma_f32_32x32x16_bf16 v[16:31], v[48:51], v[8:11], v[16:31]
	v_exp_f32_e32 v104, v104
	v_exp_f32_e32 v105, v105
	v_exp_f32_e32 v106, v106
	v_exp_f32_e32 v107, v107
	s_waitcnt lgkmcnt(0)
	v_mfma_f32_32x32x16_bf16 v[32:47], v[48:51], v[2:5], v[32:47]
	v_exp_f32_e32 v108, v108
	v_exp_f32_e32 v109, v109
	v_exp_f32_e32 v110, v110
	v_exp_f32_e32 v111, v111
	s_nop 0
	v_add_f32_e32 v2, v80, v96
	v_add_f32_e32 v2, 0, v2
	v_add_f32_e32 v3, v81, v97
	v_add_f32_e32 v2, v3, v2
	v_add_f32_e32 v3, v82, v98
	v_add_f32_e32 v2, v3, v2
	v_add_f32_e32 v3, v83, v99
	v_add_f32_e32 v2, v3, v2
	v_add_f32_e32 v3, v84, v100
	v_add_f32_e32 v2, v3, v2
	v_add_f32_e32 v3, v85, v101
	v_add_f32_e32 v2, v3, v2
	v_add_f32_e32 v3, v86, v102
	v_add_f32_e32 v2, v3, v2
	v_add_f32_e32 v3, v87, v103
	v_add_f32_e32 v2, v3, v2
	v_add_f32_e32 v3, v88, v104
	v_add_f32_e32 v2, v3, v2
	v_add_f32_e32 v3, v89, v105
	v_add_f32_e32 v2, v3, v2
	v_add_f32_e32 v3, v90, v106
	v_add_f32_e32 v2, v3, v2
	v_add_f32_e32 v3, v91, v107
	v_add_f32_e32 v2, v3, v2
	v_add_f32_e32 v3, v92, v108
	v_add_f32_e32 v2, v3, v2
	v_add_f32_e32 v3, v93, v109
	v_add_f32_e32 v2, v3, v2
	v_add_f32_e32 v3, v94, v110
	v_add_f32_e32 v2, v3, v2
	v_add_f32_e32 v3, v95, v111
	v_lshl_add_u32 v1, s8, 14, v1
	v_add_f32_e32 v7, v3, v2
	v_cvt_pk_bf16_f32 v8, v80, v81
	v_cvt_pk_bf16_f32 v9, v82, v83
	v_cvt_pk_bf16_f32 v10, v84, v85
	v_cvt_pk_bf16_f32 v11, v86, v87
	v_cvt_pk_bf16_f32 v48, v88, v89
	v_cvt_pk_bf16_f32 v49, v90, v91
	v_cvt_pk_bf16_f32 v50, v92, v93
	v_cvt_pk_bf16_f32 v51, v94, v95
	v_cvt_pk_bf16_f32 v52, v96, v97
	v_cvt_pk_bf16_f32 v53, v98, v99
	v_cvt_pk_bf16_f32 v54, v100, v101
	v_cvt_pk_bf16_f32 v55, v102, v103
	v_cvt_pk_bf16_f32 v2, v104, v105
	v_cvt_pk_bf16_f32 v3, v106, v107
	v_cvt_pk_bf16_f32 v4, v108, v109
	v_cvt_pk_bf16_f32 v5, v110, v111
	ds_read_b64_tr_b16 v[56:57], v1
	ds_read_b64_tr_b16 v[58:59], v1 offset:1024
	s_waitcnt lgkmcnt(0)
	v_mfma_f32_32x32x16_bf16 v[16:31], v[8:11], v[56:59], v[16:31]
	ds_read_b64_tr_b16 v[56:57], v1 offset:512
	ds_read_b64_tr_b16 v[58:59], v1 offset:1536
	s_waitcnt lgkmcnt(0)
	v_mfma_f32_32x32x16_bf16 v[32:47], v[8:11], v[56:59], v[32:47]
	ds_read_b64_tr_b16 v[8:9], v1 offset:2048
	ds_read_b64_tr_b16 v[10:11], v1 offset:3072
	s_waitcnt lgkmcnt(0)
	v_mfma_f32_32x32x16_bf16 v[16:31], v[48:51], v[8:11], v[16:31]
	ds_read_b64_tr_b16 v[8:9], v1 offset:2560
	ds_read_b64_tr_b16 v[10:11], v1 offset:3584
	s_waitcnt lgkmcnt(0)
	v_mfma_f32_32x32x16_bf16 v[32:47], v[48:51], v[8:11], v[32:47]
	ds_read_b64_tr_b16 v[8:9], v1 offset:4096
	ds_read_b64_tr_b16 v[10:11], v1 offset:5120
	s_waitcnt lgkmcnt(0)
	v_mfma_f32_32x32x16_bf16 v[16:31], v[52:55], v[8:11], v[16:31]
	ds_read_b64_tr_b16 v[8:9], v1 offset:4608
	ds_read_b64_tr_b16 v[10:11], v1 offset:5632
	s_waitcnt lgkmcnt(0)
	v_mfma_f32_32x32x16_bf16 v[32:47], v[52:55], v[8:11], v[32:47]
	ds_read_b64_tr_b16 v[8:9], v1 offset:6144
	ds_read_b64_tr_b16 v[10:11], v1 offset:7168
	s_waitcnt lgkmcnt(0)
	v_mfma_f32_32x32x16_bf16 v[16:31], v[2:5], v[8:11], v[16:31]
	ds_read_b64_tr_b16 v[8:9], v1 offset:6656
	ds_read_b64_tr_b16 v[10:11], v1 offset:7680
	v_add_f32_e32 v1, v14, v6
	v_add_f32_e32 v1, v1, v7
	s_waitcnt lgkmcnt(0)
	v_mfma_f32_32x32x16_bf16 v[32:47], v[2:5], v[8:11], v[32:47]
	v_mov_b32_e32 v2, v1
	s_nop 1
	v_permlane32_swap_b32_e32 v1, v2
	s_and_saveexec_b64 s[6:7], vcc
	v_lshl_add_u32 v3, v132, 2, s49
	v_add_f32_e32 v1, v1, v2
	ds_write_b32 v3, v1
	s_or_b64 exec, exec, s[6:7]
	v_and_b32_e32 v1, 14, v230
	v_and_b32_e32 v2, 1, v230
	v_bfe_u32 v3, v230, 4, 2
	v_cmp_eq_u32_e64 s[98:99], 0, v1
	v_lshlrev_b32_e32 v2, 6, v2
	v_lshl_add_u32 v2, v3, 4, v2
	v_add_u32_e32 v2, s49, v2
	s_and_saveexec_b64 s[100:101], s[98:99]
	ds_add_f32 v2, v144
	ds_add_f32 v2, v145 offset:4
	ds_add_f32 v2, v146 offset:8
	ds_add_f32 v2, v147 offset:12
	s_or_b64 exec, exec, s[100:101]
	s_add_i32 s6, s43, s14
	s_ashr_i32 s7, s6, 31
	s_lshl_b64 s[6:7], s[6:7], 11
	s_mov_b64 s[8:9], s[34:35]
	s_add_u32 s6, s8, s6
	s_addc_u32 s7, s9, s7
	s_lshl_b32 s8, s72, 7
	s_waitcnt lgkmcnt(0)
	s_add_u32 s6, s6, s8
	s_addc_u32 s7, s7, 0
	v_lshlrev_b32_e32 v2, 1, v132
	v_mov_b32_e32 v3, v0
	v_lshl_add_u64 v[2:3], s[6:7], 0, v[2:3]
	v_add_u32_e32 v152, s49, v148
	s_branch .LBB0_491

; __global__ void __launch_bounds__(NWAVES * 64, 2) fwd_megakernel(Params P) {
	.amdhsa_kernel _Z14fwd_megakernel6Params
		.amdhsa_group_segment_fixed_size 0
		.amdhsa_private_segment_fixed_size 0
		.amdhsa_kernarg_size 448
		.amdhsa_user_sgpr_count 2
		.amdhsa_user_sgpr_dispatch_ptr 0
		.amdhsa_user_sgpr_queue_ptr 0
		.amdhsa_user_sgpr_kernarg_segment_ptr 1
		.amdhsa_user_sgpr_dispatch_id 0
		.amdhsa_user_sgpr_kernarg_preload_length 0
		.amdhsa_user_sgpr_kernarg_preload_offset 0
		.amdhsa_user_sgpr_private_segment_size 0
		.amdhsa_uses_dynamic_stack 0
		.amdhsa_enable_private_segment 0
		.amdhsa_system_sgpr_workgroup_id_x 1
		.amdhsa_system_sgpr_workgroup_id_y 0
		.amdhsa_system_sgpr_workgroup_id_z 0
		.amdhsa_system_sgpr_workgroup_info 0
		.amdhsa_system_vgpr_workitem_id 2
		.amdhsa_next_free_vgpr 255
		.amdhsa_next_free_sgpr 102
		.amdhsa_accum_offset 256
		.amdhsa_reserve_vcc 1
		.amdhsa_float_round_mode_32 0
		.amdhsa_float_round_mode_16_64 0
		.amdhsa_float_denorm_mode_32 3
		.amdhsa_float_denorm_mode_16_64 3
		.amdhsa_dx10_clamp 1
		.amdhsa_ieee_mode 1
		.amdhsa_fp16_overflow 0
		.amdhsa_tg_split 0
		.amdhsa_exception_fp_ieee_invalid_op 0
		.amdhsa_exception_fp_denorm_src 0
		.amdhsa_exception_fp_ieee_div_zero 0
		.amdhsa_exception_fp_ieee_overflow 0
		.amdhsa_exception_fp_ieee_underflow 0
		.amdhsa_exception_fp_ieee_inexact 0
		.amdhsa_exception_int_div_zero 0
	.end_amdhsa_kernel

; __global__ void __launch_bounds__(NWAVES * 64, 2) fwd_megakernel(Params P) {
amdhsa.kernels:
  - .agpr_count:     0
    .args:
      - .offset:         0
        .size:           192
        .value_kind:     by_value
      - .offset:         192
        .size:           4
        .value_kind:     hidden_block_count_x
      - .offset:         196
        .size:           4
        .value_kind:     hidden_block_count_y
      - .offset:         200
        .size:           4
        .value_kind:     hidden_block_count_z
      - .offset:         204
        .size:           2
        .value_kind:     hidden_group_size_x
      - .offset:         206
        .size:           2
        .value_kind:     hidden_group_size_y
      - .offset:         208
        .size:           2
        .value_kind:     hidden_group_size_z
      - .offset:         210
        .size:           2
        .value_kind:     hidden_remainder_x
      - .offset:         212
        .size:           2
        .value_kind:     hidden_remainder_y
      - .offset:         214
        .size:           2
        .value_kind:     hidden_remainder_z
      - .offset:         232
        .size:           8
        .value_kind:     hidden_global_offset_x
      - .offset:         240
        .size:           8
        .value_kind:     hidden_global_offset_y
      - .offset:         248
        .size:           8
        .value_kind:     hidden_global_offset_z
      - .offset:         256
        .size:           2
        .value_kind:     hidden_grid_dims
      - .offset:         280
        .size:           8
        .value_kind:     hidden_multigrid_sync_arg
      - .offset:         312
        .size:           4
        .value_kind:     hidden_dynamic_lds_size
    .group_segment_fixed_size: 0
    .kernarg_segment_align: 8
    .kernarg_segment_size: 448
    .language:       OpenCL C
    .language_version:
      - 2
      - 0
    .max_flat_workgroup_size: 512
    .name:           _Z14fwd_megakernel6Params
    .private_segment_fixed_size: 0
    .sgpr_count:     108
    .sgpr_spill_count: 55
    .symbol:         _Z14fwd_megakernel6Params.kd
    .uniform_work_group_size: 1
    .uses_dynamic_stack: false
    .vgpr_count:     255
    .vgpr_spill_count: 0
    .wavefront_size: 64
